# DN scan: 16-step chunk fully unrolled with immediate LDS offsets, bf16 store via v_cvt_pk + global_store_short with SGPR base and precomputed per-lane offsets (55 instr/step, no loop/pointer overhead)
# speedup vs baseline: 1.0217x; 1.0217x over previous
.LBB0_897:
	s_or_b64 exec, exec, s[14:15]
	s_waitcnt lgkmcnt(0)
	s_barrier
	s_and_saveexec_b64 s[6:7], s[44:45]
	s_xor_b64 s[14:15], exec, s[6:7]
	s_cbranch_execz .LBB0_920
	s_setprio 3
	v_readlane_b32 s2, v255, 3
	s_add_u32 s2, s12, s2
	s_addc_u32 s3, s13, 0
	v_lshlrev_b32_e32 v0, 4, v75
	s_waitcnt vmcnt(21)
	v_bfe_u32 v5, v74, 2, 4
	s_lshl_b32 s4, s23, 1
	s_waitcnt vmcnt(20)
	v_and_or_b32 v6, v0, 48, v5
	s_add_u32 s6, s2, s4
	s_addc_u32 s7, s3, 0
	v_lshlrev_b32_e32 v0, 1, v6
	v_lshl_add_u64 v[2:3], s[6:7], 0, v[0:1]
	s_mov_b64 s[2:3], 0x10235800
	v_lshl_add_u64 v[76:77], v[2:3], 0, s[2:3]
	v_lshlrev_b32_e32 v0, 2, v5
	s_movk_i32 s2, 0xc0
	v_and_b32_e32 v4, 3, v74
	v_and_or_b32 v96, v74, s2, v0
	v_mov_b32_e32 v74, 0
	v_lshlrev_b32_e32 v94, 6, v4
	v_lshlrev_b32_e32 v95, 2, v6
	s_mov_b32 s4, 0
	v_cmp_eq_u32_e64 s[44:45], 0, v4
	v_add_u32_e32 v97, 0x520, v96
	v_mov_b32_e32 v75, v74
	v_mov_b32_e32 v78, v74
	v_mov_b32_e32 v79, v74
	v_mov_b32_e32 v80, v74
	v_mov_b32_e32 v81, v74
	v_mov_b32_e32 v82, v74
	v_mov_b32_e32 v83, v74
	v_mov_b32_e32 v84, v74
	v_mov_b32_e32 v85, v74
	v_mov_b32_e32 v86, v74
	v_mov_b32_e32 v87, v74
	v_mov_b32_e32 v88, v74
	v_mov_b32_e32 v89, v74
	v_mov_b32_e32 v90, v74
	v_mov_b32_e32 v91, v74
	s_waitcnt vmcnt(0)
	v_readfirstlane_b32 s100, v76
	s_lshl_b32 s101, s24, 9
	s_cmp_lt_i32 s24, 0
	s_cselect_b32 m0, 0x1e00, 0
	v_subrev_u32_e32 v160, s100, v76
	v_add_u32_e32 v144, m0, v160
	v_add_u32_e32 v145, s101, v144
	v_add_u32_e32 v146, s101, v145
	v_add_u32_e32 v147, s101, v146
	v_add_u32_e32 v148, s101, v147
	v_add_u32_e32 v149, s101, v148
	v_add_u32_e32 v150, s101, v149
	v_add_u32_e32 v151, s101, v150
	v_add_u32_e32 v152, s101, v151
	v_add_u32_e32 v153, s101, v152
	v_add_u32_e32 v154, s101, v153
	v_add_u32_e32 v155, s101, v154
	v_add_u32_e32 v156, s101, v155
	v_add_u32_e32 v157, s101, v156
	v_add_u32_e32 v158, s101, v157
	v_add_u32_e32 v159, s101, v158
	s_branch .LBB0_900

.LBB0_906:
	v_readfirstlane_b32 s100, v92
	v_readfirstlane_b32 s101, v93
	s_sub_u32 s100, s100, m0
	s_subb_u32 s101, s101, 0
	s_waitcnt lgkmcnt(0)
	v_pk_fma_f32 v[106:107], v[74:75], v[2:3], 0 op_sel_hi:[1,1,0]
	v_pk_fma_f32 v[108:109], v[74:75], v[30:31], 0 op_sel_hi:[1,1,0]
	ds_read_b128 v[66:69], v94 offset:800
	v_pk_fma_f32 v[106:107], v[78:79], v[4:5], v[106:107]
	v_pk_fma_f32 v[108:109], v[78:79], v[32:33], v[108:109]
	ds_read_b128 v[62:65], v94 offset:816
	v_pk_fma_f32 v[106:107], v[80:81], v[6:7], v[106:107]
	v_pk_fma_f32 v[108:109], v[80:81], v[26:27], v[108:109]
	ds_read_b128 v[58:61], v94 offset:832
	v_pk_fma_f32 v[106:107], v[82:83], v[8:9], v[106:107]
	v_pk_fma_f32 v[108:109], v[82:83], v[28:29], v[108:109]
	ds_read_b128 v[54:57], v94 offset:848
	v_pk_fma_f32 v[106:107], v[84:85], v[14:15], v[106:107]
	v_pk_fma_f32 v[108:109], v[84:85], v[22:23], v[108:109]
	ds_read_b128 v[50:53], v94 offset:1056
	v_pk_fma_f32 v[106:107], v[86:87], v[16:17], v[106:107]
	v_pk_fma_f32 v[108:109], v[86:87], v[24:25], v[108:109]
	ds_read_b128 v[46:49], v94 offset:1072
	v_pk_fma_f32 v[106:107], v[88:89], v[10:11], v[106:107]
	v_pk_fma_f32 v[108:109], v[88:89], v[18:19], v[108:109]
	ds_read_b128 v[42:45], v94 offset:1088
	v_pk_fma_f32 v[106:107], v[90:91], v[12:13], v[106:107]
	v_pk_fma_f32 v[108:109], v[90:91], v[20:21], v[108:109]
	ds_read_b128 v[38:41], v94 offset:1104
	v_add_f32_e32 v130, v106, v107
	v_add_f32_e32 v131, v108, v109
	v_pk_mul_f32 v[114:115], v[34:35], v[74:75] op_sel_hi:[0,1]
	v_add_f32_dpp v130, v130, v130 quad_perm:[1,0,3,2] row_mask:0xf bank_mask:0xf bound_ctrl:1
	v_add_f32_dpp v131, v131, v131 quad_perm:[1,0,3,2] row_mask:0xf bank_mask:0xf bound_ctrl:1
	v_pk_mul_f32 v[116:117], v[34:35], v[78:79] op_sel_hi:[0,1]
	v_add_f32_dpp v130, v130, v130 quad_perm:[2,3,0,1] row_mask:0xf bank_mask:0xf bound_ctrl:1
	v_add_f32_dpp v131, v131, v131 quad_perm:[2,3,0,1] row_mask:0xf bank_mask:0xf bound_ctrl:1
	ds_read_b32 v0, v95 offset:1312
	v_fma_f32 v130, -v34, v130, v73
	ds_read_b96 v[70:72], v1 offset:1568
	v_mul_f32_e32 v130, v35, v130
	v_mul_f32_e32 v131, v34, v131
	v_pk_mul_f32 v[118:119], v[34:35], v[80:81] op_sel_hi:[0,1]
	v_fma_f32 v131, v36, v130, v131
	v_pk_mul_f32 v[120:121], v[34:35], v[82:83] op_sel_hi:[0,1]
	v_cvt_pk_bf16_f32 v132, v131, v131
	v_pk_mul_f32 v[122:123], v[34:35], v[84:85] op_sel_hi:[0,1]
	v_pk_mul_f32 v[124:125], v[34:35], v[86:87] op_sel_hi:[0,1]
	global_store_short v144, v132, s[100:101]
	v_pk_mul_f32 v[126:127], v[34:35], v[88:89] op_sel_hi:[0,1]
	v_pk_mul_f32 v[128:129], v[34:35], v[90:91] op_sel_hi:[0,1]
	v_pk_fma_f32 v[74:75], v[2:3], v[130:131], v[114:115] op_sel_hi:[1,0,1]
	v_pk_fma_f32 v[78:79], v[4:5], v[130:131], v[116:117] op_sel_hi:[1,0,1]
	v_pk_fma_f32 v[80:81], v[6:7], v[130:131], v[118:119] op_sel_hi:[1,0,1]
	v_pk_fma_f32 v[82:83], v[8:9], v[130:131], v[120:121] op_sel_hi:[1,0,1]
	v_pk_fma_f32 v[84:85], v[14:15], v[130:131], v[122:123] op_sel_hi:[1,0,1]
	v_pk_fma_f32 v[86:87], v[16:17], v[130:131], v[124:125] op_sel_hi:[1,0,1]
	v_pk_fma_f32 v[88:89], v[10:11], v[130:131], v[126:127] op_sel_hi:[1,0,1]
	v_pk_fma_f32 v[90:91], v[12:13], v[130:131], v[128:129] op_sel_hi:[1,0,1]
	s_waitcnt lgkmcnt(0)
	v_pk_fma_f32 v[110:111], v[74:75], v[50:51], 0 op_sel_hi:[1,1,0]
	v_pk_fma_f32 v[112:113], v[74:75], v[66:67], 0 op_sel_hi:[1,1,0]
	ds_read_b128 v[30:33], v94 offset:1600
	v_pk_fma_f32 v[110:111], v[78:79], v[52:53], v[110:111]
	v_pk_fma_f32 v[112:113], v[78:79], v[68:69], v[112:113]
	ds_read_b128 v[26:29], v94 offset:1616
	v_pk_fma_f32 v[110:111], v[80:81], v[46:47], v[110:111]
	v_pk_fma_f32 v[112:113], v[80:81], v[62:63], v[112:113]
	ds_read_b128 v[22:25], v94 offset:1632
	v_pk_fma_f32 v[110:111], v[82:83], v[48:49], v[110:111]
	v_pk_fma_f32 v[112:113], v[82:83], v[64:65], v[112:113]
	ds_read_b128 v[18:21], v94 offset:1648
	v_pk_fma_f32 v[110:111], v[84:85], v[42:43], v[110:111]
	v_pk_fma_f32 v[112:113], v[84:85], v[58:59], v[112:113]
	ds_read_b128 v[2:5], v94 offset:1856
	v_pk_fma_f32 v[110:111], v[86:87], v[44:45], v[110:111]
	v_pk_fma_f32 v[112:113], v[86:87], v[60:61], v[112:113]
	ds_read_b128 v[6:9], v94 offset:1872
	v_pk_fma_f32 v[110:111], v[88:89], v[38:39], v[110:111]
	v_pk_fma_f32 v[112:113], v[88:89], v[54:55], v[112:113]
	ds_read_b128 v[14:17], v94 offset:1888
	v_pk_fma_f32 v[110:111], v[90:91], v[40:41], v[110:111]
	v_pk_fma_f32 v[112:113], v[90:91], v[56:57], v[112:113]
	ds_read_b128 v[10:13], v94 offset:1904
	v_add_f32_e32 v134, v110, v111
	v_add_f32_e32 v135, v112, v113
	v_pk_mul_f32 v[114:115], v[70:71], v[74:75] op_sel_hi:[0,1]
	v_add_f32_dpp v134, v134, v134 quad_perm:[1,0,3,2] row_mask:0xf bank_mask:0xf bound_ctrl:1
	v_add_f32_dpp v135, v135, v135 quad_perm:[1,0,3,2] row_mask:0xf bank_mask:0xf bound_ctrl:1
	v_pk_mul_f32 v[116:117], v[70:71], v[78:79] op_sel_hi:[0,1]
	v_add_f32_dpp v134, v134, v134 quad_perm:[2,3,0,1] row_mask:0xf bank_mask:0xf bound_ctrl:1
	v_add_f32_dpp v135, v135, v135 quad_perm:[2,3,0,1] row_mask:0xf bank_mask:0xf bound_ctrl:1
	ds_read_b32 v73, v95 offset:2112
	v_fma_f32 v134, -v70, v134, v0
	ds_read_b96 v[34:36], v1 offset:2368
	v_mul_f32_e32 v134, v71, v134
	v_mul_f32_e32 v135, v70, v135
	v_pk_mul_f32 v[118:119], v[70:71], v[80:81] op_sel_hi:[0,1]
	v_fma_f32 v135, v72, v134, v135
	v_pk_mul_f32 v[120:121], v[70:71], v[82:83] op_sel_hi:[0,1]
	v_cvt_pk_bf16_f32 v133, v135, v135
	v_pk_mul_f32 v[122:123], v[70:71], v[84:85] op_sel_hi:[0,1]
	v_pk_mul_f32 v[124:125], v[70:71], v[86:87] op_sel_hi:[0,1]
	global_store_short v145, v133, s[100:101]
	v_pk_mul_f32 v[126:127], v[70:71], v[88:89] op_sel_hi:[0,1]
	v_pk_mul_f32 v[128:129], v[70:71], v[90:91] op_sel_hi:[0,1]
	v_pk_fma_f32 v[74:75], v[50:51], v[134:135], v[114:115] op_sel_hi:[1,0,1]
	v_pk_fma_f32 v[78:79], v[52:53], v[134:135], v[116:117] op_sel_hi:[1,0,1]
	v_pk_fma_f32 v[80:81], v[46:47], v[134:135], v[118:119] op_sel_hi:[1,0,1]
	v_pk_fma_f32 v[82:83], v[48:49], v[134:135], v[120:121] op_sel_hi:[1,0,1]
	v_pk_fma_f32 v[84:85], v[42:43], v[134:135], v[122:123] op_sel_hi:[1,0,1]
	v_pk_fma_f32 v[86:87], v[44:45], v[134:135], v[124:125] op_sel_hi:[1,0,1]
	v_pk_fma_f32 v[88:89], v[38:39], v[134:135], v[126:127] op_sel_hi:[1,0,1]
	v_pk_fma_f32 v[90:91], v[40:41], v[134:135], v[128:129] op_sel_hi:[1,0,1]
	s_waitcnt lgkmcnt(0)
	v_pk_fma_f32 v[106:107], v[74:75], v[2:3], 0 op_sel_hi:[1,1,0]
	v_pk_fma_f32 v[108:109], v[74:75], v[30:31], 0 op_sel_hi:[1,1,0]
	ds_read_b128 v[66:69], v94 offset:2400
	v_pk_fma_f32 v[106:107], v[78:79], v[4:5], v[106:107]
	v_pk_fma_f32 v[108:109], v[78:79], v[32:33], v[108:109]
	ds_read_b128 v[62:65], v94 offset:2416
	v_pk_fma_f32 v[106:107], v[80:81], v[6:7], v[106:107]
	v_pk_fma_f32 v[108:109], v[80:81], v[26:27], v[108:109]
	ds_read_b128 v[58:61], v94 offset:2432
	v_pk_fma_f32 v[106:107], v[82:83], v[8:9], v[106:107]
	v_pk_fma_f32 v[108:109], v[82:83], v[28:29], v[108:109]
	ds_read_b128 v[54:57], v94 offset:2448
	v_pk_fma_f32 v[106:107], v[84:85], v[14:15], v[106:107]
	v_pk_fma_f32 v[108:109], v[84:85], v[22:23], v[108:109]
	ds_read_b128 v[50:53], v94 offset:2656
	v_pk_fma_f32 v[106:107], v[86:87], v[16:17], v[106:107]
	v_pk_fma_f32 v[108:109], v[86:87], v[24:25], v[108:109]
	ds_read_b128 v[46:49], v94 offset:2672
	v_pk_fma_f32 v[106:107], v[88:89], v[10:11], v[106:107]
	v_pk_fma_f32 v[108:109], v[88:89], v[18:19], v[108:109]
	ds_read_b128 v[42:45], v94 offset:2688
	v_pk_fma_f32 v[106:107], v[90:91], v[12:13], v[106:107]
	v_pk_fma_f32 v[108:109], v[90:91], v[20:21], v[108:109]
	ds_read_b128 v[38:41], v94 offset:2704
	v_add_f32_e32 v130, v106, v107
	v_add_f32_e32 v131, v108, v109
	v_pk_mul_f32 v[114:115], v[34:35], v[74:75] op_sel_hi:[0,1]
	v_add_f32_dpp v130, v130, v130 quad_perm:[1,0,3,2] row_mask:0xf bank_mask:0xf bound_ctrl:1
	v_add_f32_dpp v131, v131, v131 quad_perm:[1,0,3,2] row_mask:0xf bank_mask:0xf bound_ctrl:1
	v_pk_mul_f32 v[116:117], v[34:35], v[78:79] op_sel_hi:[0,1]
	v_add_f32_dpp v130, v130, v130 quad_perm:[2,3,0,1] row_mask:0xf bank_mask:0xf bound_ctrl:1
	v_add_f32_dpp v131, v131, v131 quad_perm:[2,3,0,1] row_mask:0xf bank_mask:0xf bound_ctrl:1
	ds_read_b32 v0, v95 offset:2912
	v_fma_f32 v130, -v34, v130, v73
	ds_read_b96 v[70:72], v1 offset:3168
	v_mul_f32_e32 v130, v35, v130
	v_mul_f32_e32 v131, v34, v131
	v_pk_mul_f32 v[118:119], v[34:35], v[80:81] op_sel_hi:[0,1]
	v_fma_f32 v131, v36, v130, v131
	v_pk_mul_f32 v[120:121], v[34:35], v[82:83] op_sel_hi:[0,1]
	v_cvt_pk_bf16_f32 v132, v131, v131
	v_pk_mul_f32 v[122:123], v[34:35], v[84:85] op_sel_hi:[0,1]
	v_pk_mul_f32 v[124:125], v[34:35], v[86:87] op_sel_hi:[0,1]
	global_store_short v146, v132, s[100:101]
	v_pk_mul_f32 v[126:127], v[34:35], v[88:89] op_sel_hi:[0,1]
	v_pk_mul_f32 v[128:129], v[34:35], v[90:91] op_sel_hi:[0,1]
	v_pk_fma_f32 v[74:75], v[2:3], v[130:131], v[114:115] op_sel_hi:[1,0,1]
	v_pk_fma_f32 v[78:79], v[4:5], v[130:131], v[116:117] op_sel_hi:[1,0,1]
	v_pk_fma_f32 v[80:81], v[6:7], v[130:131], v[118:119] op_sel_hi:[1,0,1]
	v_pk_fma_f32 v[82:83], v[8:9], v[130:131], v[120:121] op_sel_hi:[1,0,1]
	v_pk_fma_f32 v[84:85], v[14:15], v[130:131], v[122:123] op_sel_hi:[1,0,1]
	v_pk_fma_f32 v[86:87], v[16:17], v[130:131], v[124:125] op_sel_hi:[1,0,1]
	v_pk_fma_f32 v[88:89], v[10:11], v[130:131], v[126:127] op_sel_hi:[1,0,1]
	v_pk_fma_f32 v[90:91], v[12:13], v[130:131], v[128:129] op_sel_hi:[1,0,1]
	s_waitcnt lgkmcnt(0)
	v_pk_fma_f32 v[110:111], v[74:75], v[50:51], 0 op_sel_hi:[1,1,0]
	v_pk_fma_f32 v[112:113], v[74:75], v[66:67], 0 op_sel_hi:[1,1,0]
	ds_read_b128 v[30:33], v94 offset:3200
	v_pk_fma_f32 v[110:111], v[78:79], v[52:53], v[110:111]
	v_pk_fma_f32 v[112:113], v[78:79], v[68:69], v[112:113]
	ds_read_b128 v[26:29], v94 offset:3216
	v_pk_fma_f32 v[110:111], v[80:81], v[46:47], v[110:111]
	v_pk_fma_f32 v[112:113], v[80:81], v[62:63], v[112:113]
	ds_read_b128 v[22:25], v94 offset:3232
	v_pk_fma_f32 v[110:111], v[82:83], v[48:49], v[110:111]
	v_pk_fma_f32 v[112:113], v[82:83], v[64:65], v[112:113]
	ds_read_b128 v[18:21], v94 offset:3248
	v_pk_fma_f32 v[110:111], v[84:85], v[42:43], v[110:111]
	v_pk_fma_f32 v[112:113], v[84:85], v[58:59], v[112:113]
	ds_read_b128 v[2:5], v94 offset:3456
	v_pk_fma_f32 v[110:111], v[86:87], v[44:45], v[110:111]
	v_pk_fma_f32 v[112:113], v[86:87], v[60:61], v[112:113]
	ds_read_b128 v[6:9], v94 offset:3472
	v_pk_fma_f32 v[110:111], v[88:89], v[38:39], v[110:111]
	v_pk_fma_f32 v[112:113], v[88:89], v[54:55], v[112:113]
	ds_read_b128 v[14:17], v94 offset:3488
	v_pk_fma_f32 v[110:111], v[90:91], v[40:41], v[110:111]
	v_pk_fma_f32 v[112:113], v[90:91], v[56:57], v[112:113]
	ds_read_b128 v[10:13], v94 offset:3504
	v_add_f32_e32 v134, v110, v111
	v_add_f32_e32 v135, v112, v113
	v_pk_mul_f32 v[114:115], v[70:71], v[74:75] op_sel_hi:[0,1]
	v_add_f32_dpp v134, v134, v134 quad_perm:[1,0,3,2] row_mask:0xf bank_mask:0xf bound_ctrl:1
	v_add_f32_dpp v135, v135, v135 quad_perm:[1,0,3,2] row_mask:0xf bank_mask:0xf bound_ctrl:1
	v_pk_mul_f32 v[116:117], v[70:71], v[78:79] op_sel_hi:[0,1]
	v_add_f32_dpp v134, v134, v134 quad_perm:[2,3,0,1] row_mask:0xf bank_mask:0xf bound_ctrl:1
	v_add_f32_dpp v135, v135, v135 quad_perm:[2,3,0,1] row_mask:0xf bank_mask:0xf bound_ctrl:1
	ds_read_b32 v73, v95 offset:3712
	v_fma_f32 v134, -v70, v134, v0
	ds_read_b96 v[34:36], v1 offset:3968
	v_mul_f32_e32 v134, v71, v134
	v_mul_f32_e32 v135, v70, v135
	v_pk_mul_f32 v[118:119], v[70:71], v[80:81] op_sel_hi:[0,1]
	v_fma_f32 v135, v72, v134, v135
	v_pk_mul_f32 v[120:121], v[70:71], v[82:83] op_sel_hi:[0,1]
	v_cvt_pk_bf16_f32 v133, v135, v135
	v_pk_mul_f32 v[122:123], v[70:71], v[84:85] op_sel_hi:[0,1]
	v_pk_mul_f32 v[124:125], v[70:71], v[86:87] op_sel_hi:[0,1]
	global_store_short v147, v133, s[100:101]
	v_pk_mul_f32 v[126:127], v[70:71], v[88:89] op_sel_hi:[0,1]
	v_pk_mul_f32 v[128:129], v[70:71], v[90:91] op_sel_hi:[0,1]
	v_pk_fma_f32 v[74:75], v[50:51], v[134:135], v[114:115] op_sel_hi:[1,0,1]
	v_pk_fma_f32 v[78:79], v[52:53], v[134:135], v[116:117] op_sel_hi:[1,0,1]
	v_pk_fma_f32 v[80:81], v[46:47], v[134:135], v[118:119] op_sel_hi:[1,0,1]
	v_pk_fma_f32 v[82:83], v[48:49], v[134:135], v[120:121] op_sel_hi:[1,0,1]
	v_pk_fma_f32 v[84:85], v[42:43], v[134:135], v[122:123] op_sel_hi:[1,0,1]
	v_pk_fma_f32 v[86:87], v[44:45], v[134:135], v[124:125] op_sel_hi:[1,0,1]
	v_pk_fma_f32 v[88:89], v[38:39], v[134:135], v[126:127] op_sel_hi:[1,0,1]
	v_pk_fma_f32 v[90:91], v[40:41], v[134:135], v[128:129] op_sel_hi:[1,0,1]
	s_waitcnt lgkmcnt(0)
	v_pk_fma_f32 v[106:107], v[74:75], v[2:3], 0 op_sel_hi:[1,1,0]
	v_pk_fma_f32 v[108:109], v[74:75], v[30:31], 0 op_sel_hi:[1,1,0]
	ds_read_b128 v[66:69], v94 offset:4000
	v_pk_fma_f32 v[106:107], v[78:79], v[4:5], v[106:107]
	v_pk_fma_f32 v[108:109], v[78:79], v[32:33], v[108:109]
	ds_read_b128 v[62:65], v94 offset:4016
	v_pk_fma_f32 v[106:107], v[80:81], v[6:7], v[106:107]
	v_pk_fma_f32 v[108:109], v[80:81], v[26:27], v[108:109]
	ds_read_b128 v[58:61], v94 offset:4032
	v_pk_fma_f32 v[106:107], v[82:83], v[8:9], v[106:107]
	v_pk_fma_f32 v[108:109], v[82:83], v[28:29], v[108:109]
	ds_read_b128 v[54:57], v94 offset:4048
	v_pk_fma_f32 v[106:107], v[84:85], v[14:15], v[106:107]
	v_pk_fma_f32 v[108:109], v[84:85], v[22:23], v[108:109]
	ds_read_b128 v[50:53], v94 offset:4256
	v_pk_fma_f32 v[106:107], v[86:87], v[16:17], v[106:107]
	v_pk_fma_f32 v[108:109], v[86:87], v[24:25], v[108:109]
	ds_read_b128 v[46:49], v94 offset:4272
	v_pk_fma_f32 v[106:107], v[88:89], v[10:11], v[106:107]
	v_pk_fma_f32 v[108:109], v[88:89], v[18:19], v[108:109]
	ds_read_b128 v[42:45], v94 offset:4288
	v_pk_fma_f32 v[106:107], v[90:91], v[12:13], v[106:107]
	v_pk_fma_f32 v[108:109], v[90:91], v[20:21], v[108:109]
	ds_read_b128 v[38:41], v94 offset:4304
	v_add_f32_e32 v130, v106, v107
	v_add_f32_e32 v131, v108, v109
	v_pk_mul_f32 v[114:115], v[34:35], v[74:75] op_sel_hi:[0,1]
	v_add_f32_dpp v130, v130, v130 quad_perm:[1,0,3,2] row_mask:0xf bank_mask:0xf bound_ctrl:1
	v_add_f32_dpp v131, v131, v131 quad_perm:[1,0,3,2] row_mask:0xf bank_mask:0xf bound_ctrl:1
	v_pk_mul_f32 v[116:117], v[34:35], v[78:79] op_sel_hi:[0,1]
	v_add_f32_dpp v130, v130, v130 quad_perm:[2,3,0,1] row_mask:0xf bank_mask:0xf bound_ctrl:1
	v_add_f32_dpp v131, v131, v131 quad_perm:[2,3,0,1] row_mask:0xf bank_mask:0xf bound_ctrl:1
	ds_read_b32 v0, v95 offset:4512
	v_fma_f32 v130, -v34, v130, v73
	ds_read_b96 v[70:72], v1 offset:4768
	v_mul_f32_e32 v130, v35, v130
	v_mul_f32_e32 v131, v34, v131
	v_pk_mul_f32 v[118:119], v[34:35], v[80:81] op_sel_hi:[0,1]
	v_fma_f32 v131, v36, v130, v131
	v_pk_mul_f32 v[120:121], v[34:35], v[82:83] op_sel_hi:[0,1]
	v_cvt_pk_bf16_f32 v132, v131, v131
	v_pk_mul_f32 v[122:123], v[34:35], v[84:85] op_sel_hi:[0,1]
	v_pk_mul_f32 v[124:125], v[34:35], v[86:87] op_sel_hi:[0,1]
	global_store_short v148, v132, s[100:101]
	v_pk_mul_f32 v[126:127], v[34:35], v[88:89] op_sel_hi:[0,1]
	v_pk_mul_f32 v[128:129], v[34:35], v[90:91] op_sel_hi:[0,1]
	v_pk_fma_f32 v[74:75], v[2:3], v[130:131], v[114:115] op_sel_hi:[1,0,1]
	v_pk_fma_f32 v[78:79], v[4:5], v[130:131], v[116:117] op_sel_hi:[1,0,1]
	v_pk_fma_f32 v[80:81], v[6:7], v[130:131], v[118:119] op_sel_hi:[1,0,1]
	v_pk_fma_f32 v[82:83], v[8:9], v[130:131], v[120:121] op_sel_hi:[1,0,1]
	v_pk_fma_f32 v[84:85], v[14:15], v[130:131], v[122:123] op_sel_hi:[1,0,1]
	v_pk_fma_f32 v[86:87], v[16:17], v[130:131], v[124:125] op_sel_hi:[1,0,1]
	v_pk_fma_f32 v[88:89], v[10:11], v[130:131], v[126:127] op_sel_hi:[1,0,1]
	v_pk_fma_f32 v[90:91], v[12:13], v[130:131], v[128:129] op_sel_hi:[1,0,1]
	s_waitcnt lgkmcnt(0)
	v_pk_fma_f32 v[110:111], v[74:75], v[50:51], 0 op_sel_hi:[1,1,0]
	v_pk_fma_f32 v[112:113], v[74:75], v[66:67], 0 op_sel_hi:[1,1,0]
	ds_read_b128 v[30:33], v94 offset:4800
	v_pk_fma_f32 v[110:111], v[78:79], v[52:53], v[110:111]
	v_pk_fma_f32 v[112:113], v[78:79], v[68:69], v[112:113]
	ds_read_b128 v[26:29], v94 offset:4816
	v_pk_fma_f32 v[110:111], v[80:81], v[46:47], v[110:111]
	v_pk_fma_f32 v[112:113], v[80:81], v[62:63], v[112:113]
	ds_read_b128 v[22:25], v94 offset:4832
	v_pk_fma_f32 v[110:111], v[82:83], v[48:49], v[110:111]
	v_pk_fma_f32 v[112:113], v[82:83], v[64:65], v[112:113]
	ds_read_b128 v[18:21], v94 offset:4848
	v_pk_fma_f32 v[110:111], v[84:85], v[42:43], v[110:111]
	v_pk_fma_f32 v[112:113], v[84:85], v[58:59], v[112:113]
	ds_read_b128 v[2:5], v94 offset:5056
	v_pk_fma_f32 v[110:111], v[86:87], v[44:45], v[110:111]
	v_pk_fma_f32 v[112:113], v[86:87], v[60:61], v[112:113]
	ds_read_b128 v[6:9], v94 offset:5072
	v_pk_fma_f32 v[110:111], v[88:89], v[38:39], v[110:111]
	v_pk_fma_f32 v[112:113], v[88:89], v[54:55], v[112:113]
	ds_read_b128 v[14:17], v94 offset:5088
	v_pk_fma_f32 v[110:111], v[90:91], v[40:41], v[110:111]
	v_pk_fma_f32 v[112:113], v[90:91], v[56:57], v[112:113]
	ds_read_b128 v[10:13], v94 offset:5104
	v_add_f32_e32 v134, v110, v111
	v_add_f32_e32 v135, v112, v113
	v_pk_mul_f32 v[114:115], v[70:71], v[74:75] op_sel_hi:[0,1]
	v_add_f32_dpp v134, v134, v134 quad_perm:[1,0,3,2] row_mask:0xf bank_mask:0xf bound_ctrl:1
	v_add_f32_dpp v135, v135, v135 quad_perm:[1,0,3,2] row_mask:0xf bank_mask:0xf bound_ctrl:1
	v_pk_mul_f32 v[116:117], v[70:71], v[78:79] op_sel_hi:[0,1]
	v_add_f32_dpp v134, v134, v134 quad_perm:[2,3,0,1] row_mask:0xf bank_mask:0xf bound_ctrl:1
	v_add_f32_dpp v135, v135, v135 quad_perm:[2,3,0,1] row_mask:0xf bank_mask:0xf bound_ctrl:1
	ds_read_b32 v73, v95 offset:5312
	v_fma_f32 v134, -v70, v134, v0
	ds_read_b96 v[34:36], v1 offset:5568
	v_mul_f32_e32 v134, v71, v134
	v_mul_f32_e32 v135, v70, v135
	v_pk_mul_f32 v[118:119], v[70:71], v[80:81] op_sel_hi:[0,1]
	v_fma_f32 v135, v72, v134, v135
	v_pk_mul_f32 v[120:121], v[70:71], v[82:83] op_sel_hi:[0,1]
	v_cvt_pk_bf16_f32 v133, v135, v135
	v_pk_mul_f32 v[122:123], v[70:71], v[84:85] op_sel_hi:[0,1]
	v_pk_mul_f32 v[124:125], v[70:71], v[86:87] op_sel_hi:[0,1]
	global_store_short v149, v133, s[100:101]
	v_pk_mul_f32 v[126:127], v[70:71], v[88:89] op_sel_hi:[0,1]
	v_pk_mul_f32 v[128:129], v[70:71], v[90:91] op_sel_hi:[0,1]
	v_pk_fma_f32 v[74:75], v[50:51], v[134:135], v[114:115] op_sel_hi:[1,0,1]
	v_pk_fma_f32 v[78:79], v[52:53], v[134:135], v[116:117] op_sel_hi:[1,0,1]
	v_pk_fma_f32 v[80:81], v[46:47], v[134:135], v[118:119] op_sel_hi:[1,0,1]
	v_pk_fma_f32 v[82:83], v[48:49], v[134:135], v[120:121] op_sel_hi:[1,0,1]
	v_pk_fma_f32 v[84:85], v[42:43], v[134:135], v[122:123] op_sel_hi:[1,0,1]
	v_pk_fma_f32 v[86:87], v[44:45], v[134:135], v[124:125] op_sel_hi:[1,0,1]
	v_pk_fma_f32 v[88:89], v[38:39], v[134:135], v[126:127] op_sel_hi:[1,0,1]
	v_pk_fma_f32 v[90:91], v[40:41], v[134:135], v[128:129] op_sel_hi:[1,0,1]
	s_waitcnt lgkmcnt(0)
	v_pk_fma_f32 v[106:107], v[74:75], v[2:3], 0 op_sel_hi:[1,1,0]
	v_pk_fma_f32 v[108:109], v[74:75], v[30:31], 0 op_sel_hi:[1,1,0]
	ds_read_b128 v[66:69], v94 offset:5600
	v_pk_fma_f32 v[106:107], v[78:79], v[4:5], v[106:107]
	v_pk_fma_f32 v[108:109], v[78:79], v[32:33], v[108:109]
	ds_read_b128 v[62:65], v94 offset:5616
	v_pk_fma_f32 v[106:107], v[80:81], v[6:7], v[106:107]
	v_pk_fma_f32 v[108:109], v[80:81], v[26:27], v[108:109]
	ds_read_b128 v[58:61], v94 offset:5632
	v_pk_fma_f32 v[106:107], v[82:83], v[8:9], v[106:107]
	v_pk_fma_f32 v[108:109], v[82:83], v[28:29], v[108:109]
	ds_read_b128 v[54:57], v94 offset:5648
	v_pk_fma_f32 v[106:107], v[84:85], v[14:15], v[106:107]
	v_pk_fma_f32 v[108:109], v[84:85], v[22:23], v[108:109]
	ds_read_b128 v[50:53], v94 offset:5856
	v_pk_fma_f32 v[106:107], v[86:87], v[16:17], v[106:107]
	v_pk_fma_f32 v[108:109], v[86:87], v[24:25], v[108:109]
	ds_read_b128 v[46:49], v94 offset:5872
	v_pk_fma_f32 v[106:107], v[88:89], v[10:11], v[106:107]
	v_pk_fma_f32 v[108:109], v[88:89], v[18:19], v[108:109]
	ds_read_b128 v[42:45], v94 offset:5888
	v_pk_fma_f32 v[106:107], v[90:91], v[12:13], v[106:107]
	v_pk_fma_f32 v[108:109], v[90:91], v[20:21], v[108:109]
	ds_read_b128 v[38:41], v94 offset:5904
	v_add_f32_e32 v130, v106, v107
	v_add_f32_e32 v131, v108, v109
	v_pk_mul_f32 v[114:115], v[34:35], v[74:75] op_sel_hi:[0,1]
	v_add_f32_dpp v130, v130, v130 quad_perm:[1,0,3,2] row_mask:0xf bank_mask:0xf bound_ctrl:1
	v_add_f32_dpp v131, v131, v131 quad_perm:[1,0,3,2] row_mask:0xf bank_mask:0xf bound_ctrl:1
	v_pk_mul_f32 v[116:117], v[34:35], v[78:79] op_sel_hi:[0,1]
	v_add_f32_dpp v130, v130, v130 quad_perm:[2,3,0,1] row_mask:0xf bank_mask:0xf bound_ctrl:1
	v_add_f32_dpp v131, v131, v131 quad_perm:[2,3,0,1] row_mask:0xf bank_mask:0xf bound_ctrl:1
	ds_read_b32 v0, v95 offset:6112
	v_fma_f32 v130, -v34, v130, v73
	ds_read_b96 v[70:72], v1 offset:6368
	v_mul_f32_e32 v130, v35, v130
	v_mul_f32_e32 v131, v34, v131
	v_pk_mul_f32 v[118:119], v[34:35], v[80:81] op_sel_hi:[0,1]
	v_fma_f32 v131, v36, v130, v131
	v_pk_mul_f32 v[120:121], v[34:35], v[82:83] op_sel_hi:[0,1]
	v_cvt_pk_bf16_f32 v132, v131, v131
	v_pk_mul_f32 v[122:123], v[34:35], v[84:85] op_sel_hi:[0,1]
	v_pk_mul_f32 v[124:125], v[34:35], v[86:87] op_sel_hi:[0,1]
	global_store_short v150, v132, s[100:101]
	v_pk_mul_f32 v[126:127], v[34:35], v[88:89] op_sel_hi:[0,1]
	v_pk_mul_f32 v[128:129], v[34:35], v[90:91] op_sel_hi:[0,1]
	v_pk_fma_f32 v[74:75], v[2:3], v[130:131], v[114:115] op_sel_hi:[1,0,1]
	v_pk_fma_f32 v[78:79], v[4:5], v[130:131], v[116:117] op_sel_hi:[1,0,1]
	v_pk_fma_f32 v[80:81], v[6:7], v[130:131], v[118:119] op_sel_hi:[1,0,1]
	v_pk_fma_f32 v[82:83], v[8:9], v[130:131], v[120:121] op_sel_hi:[1,0,1]
	v_pk_fma_f32 v[84:85], v[14:15], v[130:131], v[122:123] op_sel_hi:[1,0,1]
	v_pk_fma_f32 v[86:87], v[16:17], v[130:131], v[124:125] op_sel_hi:[1,0,1]
	v_pk_fma_f32 v[88:89], v[10:11], v[130:131], v[126:127] op_sel_hi:[1,0,1]
	v_pk_fma_f32 v[90:91], v[12:13], v[130:131], v[128:129] op_sel_hi:[1,0,1]
	s_waitcnt lgkmcnt(0)
	v_pk_fma_f32 v[110:111], v[74:75], v[50:51], 0 op_sel_hi:[1,1,0]
	v_pk_fma_f32 v[112:113], v[74:75], v[66:67], 0 op_sel_hi:[1,1,0]
	ds_read_b128 v[30:33], v94 offset:6400
	v_pk_fma_f32 v[110:111], v[78:79], v[52:53], v[110:111]
	v_pk_fma_f32 v[112:113], v[78:79], v[68:69], v[112:113]
	ds_read_b128 v[26:29], v94 offset:6416
	v_pk_fma_f32 v[110:111], v[80:81], v[46:47], v[110:111]
	v_pk_fma_f32 v[112:113], v[80:81], v[62:63], v[112:113]
	ds_read_b128 v[22:25], v94 offset:6432
	v_pk_fma_f32 v[110:111], v[82:83], v[48:49], v[110:111]
	v_pk_fma_f32 v[112:113], v[82:83], v[64:65], v[112:113]
	ds_read_b128 v[18:21], v94 offset:6448
	v_pk_fma_f32 v[110:111], v[84:85], v[42:43], v[110:111]
	v_pk_fma_f32 v[112:113], v[84:85], v[58:59], v[112:113]
	ds_read_b128 v[2:5], v94 offset:6656
	v_pk_fma_f32 v[110:111], v[86:87], v[44:45], v[110:111]
	v_pk_fma_f32 v[112:113], v[86:87], v[60:61], v[112:113]
	ds_read_b128 v[6:9], v94 offset:6672
	v_pk_fma_f32 v[110:111], v[88:89], v[38:39], v[110:111]
	v_pk_fma_f32 v[112:113], v[88:89], v[54:55], v[112:113]
	ds_read_b128 v[14:17], v94 offset:6688
	v_pk_fma_f32 v[110:111], v[90:91], v[40:41], v[110:111]
	v_pk_fma_f32 v[112:113], v[90:91], v[56:57], v[112:113]
	ds_read_b128 v[10:13], v94 offset:6704
	v_add_f32_e32 v134, v110, v111
	v_add_f32_e32 v135, v112, v113
	v_pk_mul_f32 v[114:115], v[70:71], v[74:75] op_sel_hi:[0,1]
	v_add_f32_dpp v134, v134, v134 quad_perm:[1,0,3,2] row_mask:0xf bank_mask:0xf bound_ctrl:1
	v_add_f32_dpp v135, v135, v135 quad_perm:[1,0,3,2] row_mask:0xf bank_mask:0xf bound_ctrl:1
	v_pk_mul_f32 v[116:117], v[70:71], v[78:79] op_sel_hi:[0,1]
	v_add_f32_dpp v134, v134, v134 quad_perm:[2,3,0,1] row_mask:0xf bank_mask:0xf bound_ctrl:1
	v_add_f32_dpp v135, v135, v135 quad_perm:[2,3,0,1] row_mask:0xf bank_mask:0xf bound_ctrl:1
	ds_read_b32 v73, v95 offset:6912
	v_fma_f32 v134, -v70, v134, v0
	ds_read_b96 v[34:36], v1 offset:7168
	v_mul_f32_e32 v134, v71, v134
	v_mul_f32_e32 v135, v70, v135
	v_pk_mul_f32 v[118:119], v[70:71], v[80:81] op_sel_hi:[0,1]
	v_fma_f32 v135, v72, v134, v135
	v_pk_mul_f32 v[120:121], v[70:71], v[82:83] op_sel_hi:[0,1]
	v_cvt_pk_bf16_f32 v133, v135, v135
	v_pk_mul_f32 v[122:123], v[70:71], v[84:85] op_sel_hi:[0,1]
	v_pk_mul_f32 v[124:125], v[70:71], v[86:87] op_sel_hi:[0,1]
	global_store_short v151, v133, s[100:101]
	v_pk_mul_f32 v[126:127], v[70:71], v[88:89] op_sel_hi:[0,1]
	v_pk_mul_f32 v[128:129], v[70:71], v[90:91] op_sel_hi:[0,1]
	v_pk_fma_f32 v[74:75], v[50:51], v[134:135], v[114:115] op_sel_hi:[1,0,1]
	v_pk_fma_f32 v[78:79], v[52:53], v[134:135], v[116:117] op_sel_hi:[1,0,1]
	v_pk_fma_f32 v[80:81], v[46:47], v[134:135], v[118:119] op_sel_hi:[1,0,1]
	v_pk_fma_f32 v[82:83], v[48:49], v[134:135], v[120:121] op_sel_hi:[1,0,1]
	v_pk_fma_f32 v[84:85], v[42:43], v[134:135], v[122:123] op_sel_hi:[1,0,1]
	v_pk_fma_f32 v[86:87], v[44:45], v[134:135], v[124:125] op_sel_hi:[1,0,1]
	v_pk_fma_f32 v[88:89], v[38:39], v[134:135], v[126:127] op_sel_hi:[1,0,1]
	v_pk_fma_f32 v[90:91], v[40:41], v[134:135], v[128:129] op_sel_hi:[1,0,1]
	s_waitcnt lgkmcnt(0)
	v_pk_fma_f32 v[106:107], v[74:75], v[2:3], 0 op_sel_hi:[1,1,0]
	v_pk_fma_f32 v[108:109], v[74:75], v[30:31], 0 op_sel_hi:[1,1,0]
	ds_read_b128 v[66:69], v94 offset:7200
	v_pk_fma_f32 v[106:107], v[78:79], v[4:5], v[106:107]
	v_pk_fma_f32 v[108:109], v[78:79], v[32:33], v[108:109]
	ds_read_b128 v[62:65], v94 offset:7216
	v_pk_fma_f32 v[106:107], v[80:81], v[6:7], v[106:107]
	v_pk_fma_f32 v[108:109], v[80:81], v[26:27], v[108:109]
	ds_read_b128 v[58:61], v94 offset:7232
	v_pk_fma_f32 v[106:107], v[82:83], v[8:9], v[106:107]
	v_pk_fma_f32 v[108:109], v[82:83], v[28:29], v[108:109]
	ds_read_b128 v[54:57], v94 offset:7248
	v_pk_fma_f32 v[106:107], v[84:85], v[14:15], v[106:107]
	v_pk_fma_f32 v[108:109], v[84:85], v[22:23], v[108:109]
	ds_read_b128 v[50:53], v94 offset:7456
	v_pk_fma_f32 v[106:107], v[86:87], v[16:17], v[106:107]
	v_pk_fma_f32 v[108:109], v[86:87], v[24:25], v[108:109]
	ds_read_b128 v[46:49], v94 offset:7472
	v_pk_fma_f32 v[106:107], v[88:89], v[10:11], v[106:107]
	v_pk_fma_f32 v[108:109], v[88:89], v[18:19], v[108:109]
	ds_read_b128 v[42:45], v94 offset:7488
	v_pk_fma_f32 v[106:107], v[90:91], v[12:13], v[106:107]
	v_pk_fma_f32 v[108:109], v[90:91], v[20:21], v[108:109]
	ds_read_b128 v[38:41], v94 offset:7504
	v_add_f32_e32 v130, v106, v107
	v_add_f32_e32 v131, v108, v109
	v_pk_mul_f32 v[114:115], v[34:35], v[74:75] op_sel_hi:[0,1]
	v_add_f32_dpp v130, v130, v130 quad_perm:[1,0,3,2] row_mask:0xf bank_mask:0xf bound_ctrl:1
	v_add_f32_dpp v131, v131, v131 quad_perm:[1,0,3,2] row_mask:0xf bank_mask:0xf bound_ctrl:1
	v_pk_mul_f32 v[116:117], v[34:35], v[78:79] op_sel_hi:[0,1]
	v_add_f32_dpp v130, v130, v130 quad_perm:[2,3,0,1] row_mask:0xf bank_mask:0xf bound_ctrl:1
	v_add_f32_dpp v131, v131, v131 quad_perm:[2,3,0,1] row_mask:0xf bank_mask:0xf bound_ctrl:1
	ds_read_b32 v0, v95 offset:7712
	v_fma_f32 v130, -v34, v130, v73
	ds_read_b96 v[70:72], v1 offset:7968
	v_mul_f32_e32 v130, v35, v130
	v_mul_f32_e32 v131, v34, v131
	v_pk_mul_f32 v[118:119], v[34:35], v[80:81] op_sel_hi:[0,1]
	v_fma_f32 v131, v36, v130, v131
	v_pk_mul_f32 v[120:121], v[34:35], v[82:83] op_sel_hi:[0,1]
	v_cvt_pk_bf16_f32 v132, v131, v131
	v_pk_mul_f32 v[122:123], v[34:35], v[84:85] op_sel_hi:[0,1]
	v_pk_mul_f32 v[124:125], v[34:35], v[86:87] op_sel_hi:[0,1]
	global_store_short v152, v132, s[100:101]
	v_pk_mul_f32 v[126:127], v[34:35], v[88:89] op_sel_hi:[0,1]
	v_pk_mul_f32 v[128:129], v[34:35], v[90:91] op_sel_hi:[0,1]
	v_pk_fma_f32 v[74:75], v[2:3], v[130:131], v[114:115] op_sel_hi:[1,0,1]
	v_pk_fma_f32 v[78:79], v[4:5], v[130:131], v[116:117] op_sel_hi:[1,0,1]
	v_pk_fma_f32 v[80:81], v[6:7], v[130:131], v[118:119] op_sel_hi:[1,0,1]
	v_pk_fma_f32 v[82:83], v[8:9], v[130:131], v[120:121] op_sel_hi:[1,0,1]
	v_pk_fma_f32 v[84:85], v[14:15], v[130:131], v[122:123] op_sel_hi:[1,0,1]
	v_pk_fma_f32 v[86:87], v[16:17], v[130:131], v[124:125] op_sel_hi:[1,0,1]
	v_pk_fma_f32 v[88:89], v[10:11], v[130:131], v[126:127] op_sel_hi:[1,0,1]
	v_pk_fma_f32 v[90:91], v[12:13], v[130:131], v[128:129] op_sel_hi:[1,0,1]
	s_waitcnt lgkmcnt(0)
	v_pk_fma_f32 v[110:111], v[74:75], v[50:51], 0 op_sel_hi:[1,1,0]
	v_pk_fma_f32 v[112:113], v[74:75], v[66:67], 0 op_sel_hi:[1,1,0]
	ds_read_b128 v[30:33], v94 offset:8000
	v_pk_fma_f32 v[110:111], v[78:79], v[52:53], v[110:111]
	v_pk_fma_f32 v[112:113], v[78:79], v[68:69], v[112:113]
	ds_read_b128 v[26:29], v94 offset:8016
	v_pk_fma_f32 v[110:111], v[80:81], v[46:47], v[110:111]
	v_pk_fma_f32 v[112:113], v[80:81], v[62:63], v[112:113]
	ds_read_b128 v[22:25], v94 offset:8032
	v_pk_fma_f32 v[110:111], v[82:83], v[48:49], v[110:111]
	v_pk_fma_f32 v[112:113], v[82:83], v[64:65], v[112:113]
	ds_read_b128 v[18:21], v94 offset:8048
	v_pk_fma_f32 v[110:111], v[84:85], v[42:43], v[110:111]
	v_pk_fma_f32 v[112:113], v[84:85], v[58:59], v[112:113]
	ds_read_b128 v[2:5], v94 offset:8256
	v_pk_fma_f32 v[110:111], v[86:87], v[44:45], v[110:111]
	v_pk_fma_f32 v[112:113], v[86:87], v[60:61], v[112:113]
	ds_read_b128 v[6:9], v94 offset:8272
	v_pk_fma_f32 v[110:111], v[88:89], v[38:39], v[110:111]
	v_pk_fma_f32 v[112:113], v[88:89], v[54:55], v[112:113]
	ds_read_b128 v[14:17], v94 offset:8288
	v_pk_fma_f32 v[110:111], v[90:91], v[40:41], v[110:111]
	v_pk_fma_f32 v[112:113], v[90:91], v[56:57], v[112:113]
	ds_read_b128 v[10:13], v94 offset:8304
	v_add_f32_e32 v134, v110, v111
	v_add_f32_e32 v135, v112, v113
	v_pk_mul_f32 v[114:115], v[70:71], v[74:75] op_sel_hi:[0,1]
	v_add_f32_dpp v134, v134, v134 quad_perm:[1,0,3,2] row_mask:0xf bank_mask:0xf bound_ctrl:1
	v_add_f32_dpp v135, v135, v135 quad_perm:[1,0,3,2] row_mask:0xf bank_mask:0xf bound_ctrl:1
	v_pk_mul_f32 v[116:117], v[70:71], v[78:79] op_sel_hi:[0,1]
	v_add_f32_dpp v134, v134, v134 quad_perm:[2,3,0,1] row_mask:0xf bank_mask:0xf bound_ctrl:1
	v_add_f32_dpp v135, v135, v135 quad_perm:[2,3,0,1] row_mask:0xf bank_mask:0xf bound_ctrl:1
	ds_read_b32 v73, v95 offset:8512
	v_fma_f32 v134, -v70, v134, v0
	ds_read_b96 v[34:36], v1 offset:8768
	v_mul_f32_e32 v134, v71, v134
	v_mul_f32_e32 v135, v70, v135
	v_pk_mul_f32 v[118:119], v[70:71], v[80:81] op_sel_hi:[0,1]
	v_fma_f32 v135, v72, v134, v135
	v_pk_mul_f32 v[120:121], v[70:71], v[82:83] op_sel_hi:[0,1]
	v_cvt_pk_bf16_f32 v133, v135, v135
	v_pk_mul_f32 v[122:123], v[70:71], v[84:85] op_sel_hi:[0,1]
	v_pk_mul_f32 v[124:125], v[70:71], v[86:87] op_sel_hi:[0,1]
	global_store_short v153, v133, s[100:101]
	v_pk_mul_f32 v[126:127], v[70:71], v[88:89] op_sel_hi:[0,1]
	v_pk_mul_f32 v[128:129], v[70:71], v[90:91] op_sel_hi:[0,1]
	v_pk_fma_f32 v[74:75], v[50:51], v[134:135], v[114:115] op_sel_hi:[1,0,1]
	v_pk_fma_f32 v[78:79], v[52:53], v[134:135], v[116:117] op_sel_hi:[1,0,1]
	v_pk_fma_f32 v[80:81], v[46:47], v[134:135], v[118:119] op_sel_hi:[1,0,1]
	v_pk_fma_f32 v[82:83], v[48:49], v[134:135], v[120:121] op_sel_hi:[1,0,1]
	v_pk_fma_f32 v[84:85], v[42:43], v[134:135], v[122:123] op_sel_hi:[1,0,1]
	v_pk_fma_f32 v[86:87], v[44:45], v[134:135], v[124:125] op_sel_hi:[1,0,1]
	v_pk_fma_f32 v[88:89], v[38:39], v[134:135], v[126:127] op_sel_hi:[1,0,1]
	v_pk_fma_f32 v[90:91], v[40:41], v[134:135], v[128:129] op_sel_hi:[1,0,1]
	s_waitcnt lgkmcnt(0)
	v_pk_fma_f32 v[106:107], v[74:75], v[2:3], 0 op_sel_hi:[1,1,0]
	v_pk_fma_f32 v[108:109], v[74:75], v[30:31], 0 op_sel_hi:[1,1,0]
	ds_read_b128 v[66:69], v94 offset:8800
	v_pk_fma_f32 v[106:107], v[78:79], v[4:5], v[106:107]
	v_pk_fma_f32 v[108:109], v[78:79], v[32:33], v[108:109]
	ds_read_b128 v[62:65], v94 offset:8816
	v_pk_fma_f32 v[106:107], v[80:81], v[6:7], v[106:107]
	v_pk_fma_f32 v[108:109], v[80:81], v[26:27], v[108:109]
	ds_read_b128 v[58:61], v94 offset:8832
	v_pk_fma_f32 v[106:107], v[82:83], v[8:9], v[106:107]
	v_pk_fma_f32 v[108:109], v[82:83], v[28:29], v[108:109]
	ds_read_b128 v[54:57], v94 offset:8848
	v_pk_fma_f32 v[106:107], v[84:85], v[14:15], v[106:107]
	v_pk_fma_f32 v[108:109], v[84:85], v[22:23], v[108:109]
	ds_read_b128 v[50:53], v94 offset:9056
	v_pk_fma_f32 v[106:107], v[86:87], v[16:17], v[106:107]
	v_pk_fma_f32 v[108:109], v[86:87], v[24:25], v[108:109]
	ds_read_b128 v[46:49], v94 offset:9072
	v_pk_fma_f32 v[106:107], v[88:89], v[10:11], v[106:107]
	v_pk_fma_f32 v[108:109], v[88:89], v[18:19], v[108:109]
	ds_read_b128 v[42:45], v94 offset:9088
	v_pk_fma_f32 v[106:107], v[90:91], v[12:13], v[106:107]
	v_pk_fma_f32 v[108:109], v[90:91], v[20:21], v[108:109]
	ds_read_b128 v[38:41], v94 offset:9104
	v_add_f32_e32 v130, v106, v107
	v_add_f32_e32 v131, v108, v109
	v_pk_mul_f32 v[114:115], v[34:35], v[74:75] op_sel_hi:[0,1]
	v_add_f32_dpp v130, v130, v130 quad_perm:[1,0,3,2] row_mask:0xf bank_mask:0xf bound_ctrl:1
	v_add_f32_dpp v131, v131, v131 quad_perm:[1,0,3,2] row_mask:0xf bank_mask:0xf bound_ctrl:1
	v_pk_mul_f32 v[116:117], v[34:35], v[78:79] op_sel_hi:[0,1]
	v_add_f32_dpp v130, v130, v130 quad_perm:[2,3,0,1] row_mask:0xf bank_mask:0xf bound_ctrl:1
	v_add_f32_dpp v131, v131, v131 quad_perm:[2,3,0,1] row_mask:0xf bank_mask:0xf bound_ctrl:1
	ds_read_b32 v0, v95 offset:9312
	v_fma_f32 v130, -v34, v130, v73
	ds_read_b96 v[70:72], v1 offset:9568
	v_mul_f32_e32 v130, v35, v130
	v_mul_f32_e32 v131, v34, v131
	v_pk_mul_f32 v[118:119], v[34:35], v[80:81] op_sel_hi:[0,1]
	v_fma_f32 v131, v36, v130, v131
	v_pk_mul_f32 v[120:121], v[34:35], v[82:83] op_sel_hi:[0,1]
	v_cvt_pk_bf16_f32 v132, v131, v131
	v_pk_mul_f32 v[122:123], v[34:35], v[84:85] op_sel_hi:[0,1]
	v_pk_mul_f32 v[124:125], v[34:35], v[86:87] op_sel_hi:[0,1]
	global_store_short v154, v132, s[100:101]
	v_pk_mul_f32 v[126:127], v[34:35], v[88:89] op_sel_hi:[0,1]
	v_pk_mul_f32 v[128:129], v[34:35], v[90:91] op_sel_hi:[0,1]
	v_pk_fma_f32 v[74:75], v[2:3], v[130:131], v[114:115] op_sel_hi:[1,0,1]
	v_pk_fma_f32 v[78:79], v[4:5], v[130:131], v[116:117] op_sel_hi:[1,0,1]
	v_pk_fma_f32 v[80:81], v[6:7], v[130:131], v[118:119] op_sel_hi:[1,0,1]
	v_pk_fma_f32 v[82:83], v[8:9], v[130:131], v[120:121] op_sel_hi:[1,0,1]
	v_pk_fma_f32 v[84:85], v[14:15], v[130:131], v[122:123] op_sel_hi:[1,0,1]
	v_pk_fma_f32 v[86:87], v[16:17], v[130:131], v[124:125] op_sel_hi:[1,0,1]
	v_pk_fma_f32 v[88:89], v[10:11], v[130:131], v[126:127] op_sel_hi:[1,0,1]
	v_pk_fma_f32 v[90:91], v[12:13], v[130:131], v[128:129] op_sel_hi:[1,0,1]
	s_waitcnt lgkmcnt(0)
	v_pk_fma_f32 v[110:111], v[74:75], v[50:51], 0 op_sel_hi:[1,1,0]
	v_pk_fma_f32 v[112:113], v[74:75], v[66:67], 0 op_sel_hi:[1,1,0]
	ds_read_b128 v[30:33], v94 offset:9600
	v_pk_fma_f32 v[110:111], v[78:79], v[52:53], v[110:111]
	v_pk_fma_f32 v[112:113], v[78:79], v[68:69], v[112:113]
	ds_read_b128 v[26:29], v94 offset:9616
	v_pk_fma_f32 v[110:111], v[80:81], v[46:47], v[110:111]
	v_pk_fma_f32 v[112:113], v[80:81], v[62:63], v[112:113]
	ds_read_b128 v[22:25], v94 offset:9632
	v_pk_fma_f32 v[110:111], v[82:83], v[48:49], v[110:111]
	v_pk_fma_f32 v[112:113], v[82:83], v[64:65], v[112:113]
	ds_read_b128 v[18:21], v94 offset:9648
	v_pk_fma_f32 v[110:111], v[84:85], v[42:43], v[110:111]
	v_pk_fma_f32 v[112:113], v[84:85], v[58:59], v[112:113]
	ds_read_b128 v[2:5], v94 offset:9856
	v_pk_fma_f32 v[110:111], v[86:87], v[44:45], v[110:111]
	v_pk_fma_f32 v[112:113], v[86:87], v[60:61], v[112:113]
	ds_read_b128 v[6:9], v94 offset:9872
	v_pk_fma_f32 v[110:111], v[88:89], v[38:39], v[110:111]
	v_pk_fma_f32 v[112:113], v[88:89], v[54:55], v[112:113]
	ds_read_b128 v[14:17], v94 offset:9888
	v_pk_fma_f32 v[110:111], v[90:91], v[40:41], v[110:111]
	v_pk_fma_f32 v[112:113], v[90:91], v[56:57], v[112:113]
	ds_read_b128 v[10:13], v94 offset:9904
	v_add_f32_e32 v134, v110, v111
	v_add_f32_e32 v135, v112, v113
	v_pk_mul_f32 v[114:115], v[70:71], v[74:75] op_sel_hi:[0,1]
	v_add_f32_dpp v134, v134, v134 quad_perm:[1,0,3,2] row_mask:0xf bank_mask:0xf bound_ctrl:1
	v_add_f32_dpp v135, v135, v135 quad_perm:[1,0,3,2] row_mask:0xf bank_mask:0xf bound_ctrl:1
	v_pk_mul_f32 v[116:117], v[70:71], v[78:79] op_sel_hi:[0,1]
	v_add_f32_dpp v134, v134, v134 quad_perm:[2,3,0,1] row_mask:0xf bank_mask:0xf bound_ctrl:1
	v_add_f32_dpp v135, v135, v135 quad_perm:[2,3,0,1] row_mask:0xf bank_mask:0xf bound_ctrl:1
	ds_read_b32 v73, v95 offset:10112
	v_fma_f32 v134, -v70, v134, v0
	ds_read_b96 v[34:36], v1 offset:10368
	v_mul_f32_e32 v134, v71, v134
	v_mul_f32_e32 v135, v70, v135
	v_pk_mul_f32 v[118:119], v[70:71], v[80:81] op_sel_hi:[0,1]
	v_fma_f32 v135, v72, v134, v135
	v_pk_mul_f32 v[120:121], v[70:71], v[82:83] op_sel_hi:[0,1]
	v_cvt_pk_bf16_f32 v133, v135, v135
	v_pk_mul_f32 v[122:123], v[70:71], v[84:85] op_sel_hi:[0,1]
	v_pk_mul_f32 v[124:125], v[70:71], v[86:87] op_sel_hi:[0,1]
	global_store_short v155, v133, s[100:101]
	v_pk_mul_f32 v[126:127], v[70:71], v[88:89] op_sel_hi:[0,1]
	v_pk_mul_f32 v[128:129], v[70:71], v[90:91] op_sel_hi:[0,1]
	v_pk_fma_f32 v[74:75], v[50:51], v[134:135], v[114:115] op_sel_hi:[1,0,1]
	v_pk_fma_f32 v[78:79], v[52:53], v[134:135], v[116:117] op_sel_hi:[1,0,1]
	v_pk_fma_f32 v[80:81], v[46:47], v[134:135], v[118:119] op_sel_hi:[1,0,1]
	v_pk_fma_f32 v[82:83], v[48:49], v[134:135], v[120:121] op_sel_hi:[1,0,1]
	v_pk_fma_f32 v[84:85], v[42:43], v[134:135], v[122:123] op_sel_hi:[1,0,1]
	v_pk_fma_f32 v[86:87], v[44:45], v[134:135], v[124:125] op_sel_hi:[1,0,1]
	v_pk_fma_f32 v[88:89], v[38:39], v[134:135], v[126:127] op_sel_hi:[1,0,1]
	v_pk_fma_f32 v[90:91], v[40:41], v[134:135], v[128:129] op_sel_hi:[1,0,1]
	s_waitcnt lgkmcnt(0)
	v_pk_fma_f32 v[106:107], v[74:75], v[2:3], 0 op_sel_hi:[1,1,0]
	v_pk_fma_f32 v[108:109], v[74:75], v[30:31], 0 op_sel_hi:[1,1,0]
	ds_read_b128 v[66:69], v94 offset:10400
	v_pk_fma_f32 v[106:107], v[78:79], v[4:5], v[106:107]
	v_pk_fma_f32 v[108:109], v[78:79], v[32:33], v[108:109]
	ds_read_b128 v[62:65], v94 offset:10416
	v_pk_fma_f32 v[106:107], v[80:81], v[6:7], v[106:107]
	v_pk_fma_f32 v[108:109], v[80:81], v[26:27], v[108:109]
	ds_read_b128 v[58:61], v94 offset:10432
	v_pk_fma_f32 v[106:107], v[82:83], v[8:9], v[106:107]
	v_pk_fma_f32 v[108:109], v[82:83], v[28:29], v[108:109]
	ds_read_b128 v[54:57], v94 offset:10448
	v_pk_fma_f32 v[106:107], v[84:85], v[14:15], v[106:107]
	v_pk_fma_f32 v[108:109], v[84:85], v[22:23], v[108:109]
	ds_read_b128 v[50:53], v94 offset:10656
	v_pk_fma_f32 v[106:107], v[86:87], v[16:17], v[106:107]
	v_pk_fma_f32 v[108:109], v[86:87], v[24:25], v[108:109]
	ds_read_b128 v[46:49], v94 offset:10672
	v_pk_fma_f32 v[106:107], v[88:89], v[10:11], v[106:107]
	v_pk_fma_f32 v[108:109], v[88:89], v[18:19], v[108:109]
	ds_read_b128 v[42:45], v94 offset:10688
	v_pk_fma_f32 v[106:107], v[90:91], v[12:13], v[106:107]
	v_pk_fma_f32 v[108:109], v[90:91], v[20:21], v[108:109]
	ds_read_b128 v[38:41], v94 offset:10704
	v_add_f32_e32 v130, v106, v107
	v_add_f32_e32 v131, v108, v109
	v_pk_mul_f32 v[114:115], v[34:35], v[74:75] op_sel_hi:[0,1]
	v_add_f32_dpp v130, v130, v130 quad_perm:[1,0,3,2] row_mask:0xf bank_mask:0xf bound_ctrl:1
	v_add_f32_dpp v131, v131, v131 quad_perm:[1,0,3,2] row_mask:0xf bank_mask:0xf bound_ctrl:1
	v_pk_mul_f32 v[116:117], v[34:35], v[78:79] op_sel_hi:[0,1]
	v_add_f32_dpp v130, v130, v130 quad_perm:[2,3,0,1] row_mask:0xf bank_mask:0xf bound_ctrl:1
	v_add_f32_dpp v131, v131, v131 quad_perm:[2,3,0,1] row_mask:0xf bank_mask:0xf bound_ctrl:1
	ds_read_b32 v0, v95 offset:10912
	v_fma_f32 v130, -v34, v130, v73
	ds_read_b96 v[70:72], v1 offset:11168
	v_mul_f32_e32 v130, v35, v130
	v_mul_f32_e32 v131, v34, v131
	v_pk_mul_f32 v[118:119], v[34:35], v[80:81] op_sel_hi:[0,1]
	v_fma_f32 v131, v36, v130, v131
	v_pk_mul_f32 v[120:121], v[34:35], v[82:83] op_sel_hi:[0,1]
	v_cvt_pk_bf16_f32 v132, v131, v131
	v_pk_mul_f32 v[122:123], v[34:35], v[84:85] op_sel_hi:[0,1]
	v_pk_mul_f32 v[124:125], v[34:35], v[86:87] op_sel_hi:[0,1]
	global_store_short v156, v132, s[100:101]
	v_pk_mul_f32 v[126:127], v[34:35], v[88:89] op_sel_hi:[0,1]
	v_pk_mul_f32 v[128:129], v[34:35], v[90:91] op_sel_hi:[0,1]
	v_pk_fma_f32 v[74:75], v[2:3], v[130:131], v[114:115] op_sel_hi:[1,0,1]
	v_pk_fma_f32 v[78:79], v[4:5], v[130:131], v[116:117] op_sel_hi:[1,0,1]
	v_pk_fma_f32 v[80:81], v[6:7], v[130:131], v[118:119] op_sel_hi:[1,0,1]
	v_pk_fma_f32 v[82:83], v[8:9], v[130:131], v[120:121] op_sel_hi:[1,0,1]
	v_pk_fma_f32 v[84:85], v[14:15], v[130:131], v[122:123] op_sel_hi:[1,0,1]
	v_pk_fma_f32 v[86:87], v[16:17], v[130:131], v[124:125] op_sel_hi:[1,0,1]
	v_pk_fma_f32 v[88:89], v[10:11], v[130:131], v[126:127] op_sel_hi:[1,0,1]
	v_pk_fma_f32 v[90:91], v[12:13], v[130:131], v[128:129] op_sel_hi:[1,0,1]
	s_waitcnt lgkmcnt(0)
	v_pk_fma_f32 v[110:111], v[74:75], v[50:51], 0 op_sel_hi:[1,1,0]
	v_pk_fma_f32 v[112:113], v[74:75], v[66:67], 0 op_sel_hi:[1,1,0]
	ds_read_b128 v[30:33], v94 offset:11200
	v_pk_fma_f32 v[110:111], v[78:79], v[52:53], v[110:111]
	v_pk_fma_f32 v[112:113], v[78:79], v[68:69], v[112:113]
	ds_read_b128 v[26:29], v94 offset:11216
	v_pk_fma_f32 v[110:111], v[80:81], v[46:47], v[110:111]
	v_pk_fma_f32 v[112:113], v[80:81], v[62:63], v[112:113]
	ds_read_b128 v[22:25], v94 offset:11232
	v_pk_fma_f32 v[110:111], v[82:83], v[48:49], v[110:111]
	v_pk_fma_f32 v[112:113], v[82:83], v[64:65], v[112:113]
	ds_read_b128 v[18:21], v94 offset:11248
	v_pk_fma_f32 v[110:111], v[84:85], v[42:43], v[110:111]
	v_pk_fma_f32 v[112:113], v[84:85], v[58:59], v[112:113]
	ds_read_b128 v[2:5], v94 offset:11456
	v_pk_fma_f32 v[110:111], v[86:87], v[44:45], v[110:111]
	v_pk_fma_f32 v[112:113], v[86:87], v[60:61], v[112:113]
	ds_read_b128 v[6:9], v94 offset:11472
	v_pk_fma_f32 v[110:111], v[88:89], v[38:39], v[110:111]
	v_pk_fma_f32 v[112:113], v[88:89], v[54:55], v[112:113]
	ds_read_b128 v[14:17], v94 offset:11488
	v_pk_fma_f32 v[110:111], v[90:91], v[40:41], v[110:111]
	v_pk_fma_f32 v[112:113], v[90:91], v[56:57], v[112:113]
	ds_read_b128 v[10:13], v94 offset:11504
	v_add_f32_e32 v134, v110, v111
	v_add_f32_e32 v135, v112, v113
	v_pk_mul_f32 v[114:115], v[70:71], v[74:75] op_sel_hi:[0,1]
	v_add_f32_dpp v134, v134, v134 quad_perm:[1,0,3,2] row_mask:0xf bank_mask:0xf bound_ctrl:1
	v_add_f32_dpp v135, v135, v135 quad_perm:[1,0,3,2] row_mask:0xf bank_mask:0xf bound_ctrl:1
	v_pk_mul_f32 v[116:117], v[70:71], v[78:79] op_sel_hi:[0,1]
	v_add_f32_dpp v134, v134, v134 quad_perm:[2,3,0,1] row_mask:0xf bank_mask:0xf bound_ctrl:1
	v_add_f32_dpp v135, v135, v135 quad_perm:[2,3,0,1] row_mask:0xf bank_mask:0xf bound_ctrl:1
	ds_read_b32 v73, v95 offset:11712
	v_fma_f32 v134, -v70, v134, v0
	ds_read_b96 v[34:36], v1 offset:11968
	v_mul_f32_e32 v134, v71, v134
	v_mul_f32_e32 v135, v70, v135
	v_pk_mul_f32 v[118:119], v[70:71], v[80:81] op_sel_hi:[0,1]
	v_fma_f32 v135, v72, v134, v135
	v_pk_mul_f32 v[120:121], v[70:71], v[82:83] op_sel_hi:[0,1]
	v_cvt_pk_bf16_f32 v133, v135, v135
	v_pk_mul_f32 v[122:123], v[70:71], v[84:85] op_sel_hi:[0,1]
	v_pk_mul_f32 v[124:125], v[70:71], v[86:87] op_sel_hi:[0,1]
	global_store_short v157, v133, s[100:101]
	v_pk_mul_f32 v[126:127], v[70:71], v[88:89] op_sel_hi:[0,1]
	v_pk_mul_f32 v[128:129], v[70:71], v[90:91] op_sel_hi:[0,1]
	v_pk_fma_f32 v[74:75], v[50:51], v[134:135], v[114:115] op_sel_hi:[1,0,1]
	v_pk_fma_f32 v[78:79], v[52:53], v[134:135], v[116:117] op_sel_hi:[1,0,1]
	v_pk_fma_f32 v[80:81], v[46:47], v[134:135], v[118:119] op_sel_hi:[1,0,1]
	v_pk_fma_f32 v[82:83], v[48:49], v[134:135], v[120:121] op_sel_hi:[1,0,1]
	v_pk_fma_f32 v[84:85], v[42:43], v[134:135], v[122:123] op_sel_hi:[1,0,1]
	v_pk_fma_f32 v[86:87], v[44:45], v[134:135], v[124:125] op_sel_hi:[1,0,1]
	v_pk_fma_f32 v[88:89], v[38:39], v[134:135], v[126:127] op_sel_hi:[1,0,1]
	v_pk_fma_f32 v[90:91], v[40:41], v[134:135], v[128:129] op_sel_hi:[1,0,1]
	s_waitcnt lgkmcnt(0)
	v_pk_fma_f32 v[106:107], v[74:75], v[2:3], 0 op_sel_hi:[1,1,0]
	v_pk_fma_f32 v[108:109], v[74:75], v[30:31], 0 op_sel_hi:[1,1,0]
	ds_read_b128 v[66:69], v94 offset:12000
	v_pk_fma_f32 v[106:107], v[78:79], v[4:5], v[106:107]
	v_pk_fma_f32 v[108:109], v[78:79], v[32:33], v[108:109]
	ds_read_b128 v[62:65], v94 offset:12016
	v_pk_fma_f32 v[106:107], v[80:81], v[6:7], v[106:107]
	v_pk_fma_f32 v[108:109], v[80:81], v[26:27], v[108:109]
	ds_read_b128 v[58:61], v94 offset:12032
	v_pk_fma_f32 v[106:107], v[82:83], v[8:9], v[106:107]
	v_pk_fma_f32 v[108:109], v[82:83], v[28:29], v[108:109]
	ds_read_b128 v[54:57], v94 offset:12048
	v_pk_fma_f32 v[106:107], v[84:85], v[14:15], v[106:107]
	v_pk_fma_f32 v[108:109], v[84:85], v[22:23], v[108:109]
	ds_read_b128 v[50:53], v94 offset:12256
	v_pk_fma_f32 v[106:107], v[86:87], v[16:17], v[106:107]
	v_pk_fma_f32 v[108:109], v[86:87], v[24:25], v[108:109]
	ds_read_b128 v[46:49], v94 offset:12272
	v_pk_fma_f32 v[106:107], v[88:89], v[10:11], v[106:107]
	v_pk_fma_f32 v[108:109], v[88:89], v[18:19], v[108:109]
	ds_read_b128 v[42:45], v94 offset:12288
	v_pk_fma_f32 v[106:107], v[90:91], v[12:13], v[106:107]
	v_pk_fma_f32 v[108:109], v[90:91], v[20:21], v[108:109]
	ds_read_b128 v[38:41], v94 offset:12304
	v_add_f32_e32 v130, v106, v107
	v_add_f32_e32 v131, v108, v109
	v_pk_mul_f32 v[114:115], v[34:35], v[74:75] op_sel_hi:[0,1]
	v_add_f32_dpp v130, v130, v130 quad_perm:[1,0,3,2] row_mask:0xf bank_mask:0xf bound_ctrl:1
	v_add_f32_dpp v131, v131, v131 quad_perm:[1,0,3,2] row_mask:0xf bank_mask:0xf bound_ctrl:1
	v_pk_mul_f32 v[116:117], v[34:35], v[78:79] op_sel_hi:[0,1]
	v_add_f32_dpp v130, v130, v130 quad_perm:[2,3,0,1] row_mask:0xf bank_mask:0xf bound_ctrl:1
	v_add_f32_dpp v131, v131, v131 quad_perm:[2,3,0,1] row_mask:0xf bank_mask:0xf bound_ctrl:1
	ds_read_b32 v0, v95 offset:12512
	v_fma_f32 v130, -v34, v130, v73
	ds_read_b96 v[70:72], v1 offset:12768
	v_mul_f32_e32 v130, v35, v130
	v_mul_f32_e32 v131, v34, v131
	v_pk_mul_f32 v[118:119], v[34:35], v[80:81] op_sel_hi:[0,1]
	v_fma_f32 v131, v36, v130, v131
	v_pk_mul_f32 v[120:121], v[34:35], v[82:83] op_sel_hi:[0,1]
	v_cvt_pk_bf16_f32 v132, v131, v131
	v_pk_mul_f32 v[122:123], v[34:35], v[84:85] op_sel_hi:[0,1]
	v_pk_mul_f32 v[124:125], v[34:35], v[86:87] op_sel_hi:[0,1]
	global_store_short v158, v132, s[100:101]
	v_pk_mul_f32 v[126:127], v[34:35], v[88:89] op_sel_hi:[0,1]
	v_pk_mul_f32 v[128:129], v[34:35], v[90:91] op_sel_hi:[0,1]
	v_pk_fma_f32 v[74:75], v[2:3], v[130:131], v[114:115] op_sel_hi:[1,0,1]
	v_pk_fma_f32 v[78:79], v[4:5], v[130:131], v[116:117] op_sel_hi:[1,0,1]
	v_pk_fma_f32 v[80:81], v[6:7], v[130:131], v[118:119] op_sel_hi:[1,0,1]
	v_pk_fma_f32 v[82:83], v[8:9], v[130:131], v[120:121] op_sel_hi:[1,0,1]
	v_pk_fma_f32 v[84:85], v[14:15], v[130:131], v[122:123] op_sel_hi:[1,0,1]
	v_pk_fma_f32 v[86:87], v[16:17], v[130:131], v[124:125] op_sel_hi:[1,0,1]
	v_pk_fma_f32 v[88:89], v[10:11], v[130:131], v[126:127] op_sel_hi:[1,0,1]
	v_pk_fma_f32 v[90:91], v[12:13], v[130:131], v[128:129] op_sel_hi:[1,0,1]
	s_waitcnt lgkmcnt(0)
	v_pk_fma_f32 v[110:111], v[74:75], v[50:51], 0 op_sel_hi:[1,1,0]
	v_pk_fma_f32 v[112:113], v[74:75], v[66:67], 0 op_sel_hi:[1,1,0]
	ds_read_b128 v[30:33], v94 offset:12800
	v_pk_fma_f32 v[110:111], v[78:79], v[52:53], v[110:111]
	v_pk_fma_f32 v[112:113], v[78:79], v[68:69], v[112:113]
	ds_read_b128 v[26:29], v94 offset:12816
	v_pk_fma_f32 v[110:111], v[80:81], v[46:47], v[110:111]
	v_pk_fma_f32 v[112:113], v[80:81], v[62:63], v[112:113]
	ds_read_b128 v[22:25], v94 offset:12832
	v_pk_fma_f32 v[110:111], v[82:83], v[48:49], v[110:111]
	v_pk_fma_f32 v[112:113], v[82:83], v[64:65], v[112:113]
	ds_read_b128 v[18:21], v94 offset:12848
	v_pk_fma_f32 v[110:111], v[84:85], v[42:43], v[110:111]
	v_pk_fma_f32 v[112:113], v[84:85], v[58:59], v[112:113]
	ds_read_b128 v[2:5], v94 offset:13056
	v_pk_fma_f32 v[110:111], v[86:87], v[44:45], v[110:111]
	v_pk_fma_f32 v[112:113], v[86:87], v[60:61], v[112:113]
	ds_read_b128 v[6:9], v94 offset:13072
	v_pk_fma_f32 v[110:111], v[88:89], v[38:39], v[110:111]
	v_pk_fma_f32 v[112:113], v[88:89], v[54:55], v[112:113]
	ds_read_b128 v[14:17], v94 offset:13088
	v_pk_fma_f32 v[110:111], v[90:91], v[40:41], v[110:111]
	v_pk_fma_f32 v[112:113], v[90:91], v[56:57], v[112:113]
	ds_read_b128 v[10:13], v94 offset:13104
	v_add_f32_e32 v134, v110, v111
	v_add_f32_e32 v135, v112, v113
	v_pk_mul_f32 v[114:115], v[70:71], v[74:75] op_sel_hi:[0,1]
	v_add_f32_dpp v134, v134, v134 quad_perm:[1,0,3,2] row_mask:0xf bank_mask:0xf bound_ctrl:1
	v_add_f32_dpp v135, v135, v135 quad_perm:[1,0,3,2] row_mask:0xf bank_mask:0xf bound_ctrl:1
	v_pk_mul_f32 v[116:117], v[70:71], v[78:79] op_sel_hi:[0,1]
	v_add_f32_dpp v134, v134, v134 quad_perm:[2,3,0,1] row_mask:0xf bank_mask:0xf bound_ctrl:1
	v_add_f32_dpp v135, v135, v135 quad_perm:[2,3,0,1] row_mask:0xf bank_mask:0xf bound_ctrl:1
	ds_read_b32 v73, v95 offset:13312
	v_fma_f32 v134, -v70, v134, v0
	ds_read_b96 v[34:36], v1 offset:13568
	v_mul_f32_e32 v134, v71, v134
	v_mul_f32_e32 v135, v70, v135
	v_pk_mul_f32 v[118:119], v[70:71], v[80:81] op_sel_hi:[0,1]
	v_fma_f32 v135, v72, v134, v135
	v_pk_mul_f32 v[120:121], v[70:71], v[82:83] op_sel_hi:[0,1]
	v_cvt_pk_bf16_f32 v133, v135, v135
	v_pk_mul_f32 v[122:123], v[70:71], v[84:85] op_sel_hi:[0,1]
	v_pk_mul_f32 v[124:125], v[70:71], v[86:87] op_sel_hi:[0,1]
	global_store_short v159, v133, s[100:101]
	v_pk_mul_f32 v[126:127], v[70:71], v[88:89] op_sel_hi:[0,1]
	v_pk_mul_f32 v[128:129], v[70:71], v[90:91] op_sel_hi:[0,1]
	v_pk_fma_f32 v[74:75], v[50:51], v[134:135], v[114:115] op_sel_hi:[1,0,1]
	v_pk_fma_f32 v[78:79], v[52:53], v[134:135], v[116:117] op_sel_hi:[1,0,1]
	v_pk_fma_f32 v[80:81], v[46:47], v[134:135], v[118:119] op_sel_hi:[1,0,1]
	v_pk_fma_f32 v[82:83], v[48:49], v[134:135], v[120:121] op_sel_hi:[1,0,1]
	v_pk_fma_f32 v[84:85], v[42:43], v[134:135], v[122:123] op_sel_hi:[1,0,1]
	v_pk_fma_f32 v[86:87], v[44:45], v[134:135], v[124:125] op_sel_hi:[1,0,1]
	v_pk_fma_f32 v[88:89], v[38:39], v[134:135], v[126:127] op_sel_hi:[1,0,1]
	v_pk_fma_f32 v[90:91], v[40:41], v[134:135], v[128:129] op_sel_hi:[1,0,1]

.LBB0_916:
	v_readfirstlane_b32 s100, v92
	v_readfirstlane_b32 s101, v93
	s_sub_u32 s100, s100, m0
	s_subb_u32 s101, s101, 0
	s_waitcnt lgkmcnt(0)
	v_pk_fma_f32 v[106:107], v[74:75], v[2:3], 0 op_sel_hi:[1,1,0]
	v_pk_fma_f32 v[108:109], v[74:75], v[30:31], 0 op_sel_hi:[1,1,0]
	ds_read_b128 v[66:69], v94 offset:13600
	v_pk_fma_f32 v[106:107], v[78:79], v[4:5], v[106:107]
	v_pk_fma_f32 v[108:109], v[78:79], v[32:33], v[108:109]
	ds_read_b128 v[62:65], v94 offset:13616
	v_pk_fma_f32 v[106:107], v[80:81], v[6:7], v[106:107]
	v_pk_fma_f32 v[108:109], v[80:81], v[26:27], v[108:109]
	ds_read_b128 v[58:61], v94 offset:13632
	v_pk_fma_f32 v[106:107], v[82:83], v[8:9], v[106:107]
	v_pk_fma_f32 v[108:109], v[82:83], v[28:29], v[108:109]
	ds_read_b128 v[54:57], v94 offset:13648
	v_pk_fma_f32 v[106:107], v[84:85], v[14:15], v[106:107]
	v_pk_fma_f32 v[108:109], v[84:85], v[22:23], v[108:109]
	ds_read_b128 v[50:53], v94 offset:13856
	v_pk_fma_f32 v[106:107], v[86:87], v[16:17], v[106:107]
	v_pk_fma_f32 v[108:109], v[86:87], v[24:25], v[108:109]
	ds_read_b128 v[46:49], v94 offset:13872
	v_pk_fma_f32 v[106:107], v[88:89], v[10:11], v[106:107]
	v_pk_fma_f32 v[108:109], v[88:89], v[18:19], v[108:109]
	ds_read_b128 v[42:45], v94 offset:13888
	v_pk_fma_f32 v[106:107], v[90:91], v[12:13], v[106:107]
	v_pk_fma_f32 v[108:109], v[90:91], v[20:21], v[108:109]
	ds_read_b128 v[38:41], v94 offset:13904
	v_add_f32_e32 v130, v106, v107
	v_add_f32_e32 v131, v108, v109
	v_pk_mul_f32 v[114:115], v[34:35], v[74:75] op_sel_hi:[0,1]
	v_add_f32_dpp v130, v130, v130 quad_perm:[1,0,3,2] row_mask:0xf bank_mask:0xf bound_ctrl:1
	v_add_f32_dpp v131, v131, v131 quad_perm:[1,0,3,2] row_mask:0xf bank_mask:0xf bound_ctrl:1
	v_pk_mul_f32 v[116:117], v[34:35], v[78:79] op_sel_hi:[0,1]
	v_add_f32_dpp v130, v130, v130 quad_perm:[2,3,0,1] row_mask:0xf bank_mask:0xf bound_ctrl:1
	v_add_f32_dpp v131, v131, v131 quad_perm:[2,3,0,1] row_mask:0xf bank_mask:0xf bound_ctrl:1
	ds_read_b32 v0, v95 offset:14112
	v_fma_f32 v130, -v34, v130, v73
	ds_read_b96 v[70:72], v1 offset:14368
	v_mul_f32_e32 v130, v35, v130
	v_mul_f32_e32 v131, v34, v131
	v_pk_mul_f32 v[118:119], v[34:35], v[80:81] op_sel_hi:[0,1]
	v_fma_f32 v131, v36, v130, v131
	v_pk_mul_f32 v[120:121], v[34:35], v[82:83] op_sel_hi:[0,1]
	v_cvt_pk_bf16_f32 v132, v131, v131
	v_pk_mul_f32 v[122:123], v[34:35], v[84:85] op_sel_hi:[0,1]
	v_pk_mul_f32 v[124:125], v[34:35], v[86:87] op_sel_hi:[0,1]
	global_store_short v144, v132, s[100:101]
	v_pk_mul_f32 v[126:127], v[34:35], v[88:89] op_sel_hi:[0,1]
	v_pk_mul_f32 v[128:129], v[34:35], v[90:91] op_sel_hi:[0,1]
	v_pk_fma_f32 v[74:75], v[2:3], v[130:131], v[114:115] op_sel_hi:[1,0,1]
	v_pk_fma_f32 v[78:79], v[4:5], v[130:131], v[116:117] op_sel_hi:[1,0,1]
	v_pk_fma_f32 v[80:81], v[6:7], v[130:131], v[118:119] op_sel_hi:[1,0,1]
	v_pk_fma_f32 v[82:83], v[8:9], v[130:131], v[120:121] op_sel_hi:[1,0,1]
	v_pk_fma_f32 v[84:85], v[14:15], v[130:131], v[122:123] op_sel_hi:[1,0,1]
	v_pk_fma_f32 v[86:87], v[16:17], v[130:131], v[124:125] op_sel_hi:[1,0,1]
	v_pk_fma_f32 v[88:89], v[10:11], v[130:131], v[126:127] op_sel_hi:[1,0,1]
	v_pk_fma_f32 v[90:91], v[12:13], v[130:131], v[128:129] op_sel_hi:[1,0,1]
	s_waitcnt lgkmcnt(0)
	v_pk_fma_f32 v[110:111], v[74:75], v[50:51], 0 op_sel_hi:[1,1,0]
	v_pk_fma_f32 v[112:113], v[74:75], v[66:67], 0 op_sel_hi:[1,1,0]
	ds_read_b128 v[30:33], v94 offset:14400
	v_pk_fma_f32 v[110:111], v[78:79], v[52:53], v[110:111]
	v_pk_fma_f32 v[112:113], v[78:79], v[68:69], v[112:113]
	ds_read_b128 v[26:29], v94 offset:14416
	v_pk_fma_f32 v[110:111], v[80:81], v[46:47], v[110:111]
	v_pk_fma_f32 v[112:113], v[80:81], v[62:63], v[112:113]
	ds_read_b128 v[22:25], v94 offset:14432
	v_pk_fma_f32 v[110:111], v[82:83], v[48:49], v[110:111]
	v_pk_fma_f32 v[112:113], v[82:83], v[64:65], v[112:113]
	ds_read_b128 v[18:21], v94 offset:14448
	v_pk_fma_f32 v[110:111], v[84:85], v[42:43], v[110:111]
	v_pk_fma_f32 v[112:113], v[84:85], v[58:59], v[112:113]
	ds_read_b128 v[2:5], v94 offset:14656
	v_pk_fma_f32 v[110:111], v[86:87], v[44:45], v[110:111]
	v_pk_fma_f32 v[112:113], v[86:87], v[60:61], v[112:113]
	ds_read_b128 v[6:9], v94 offset:14672
	v_pk_fma_f32 v[110:111], v[88:89], v[38:39], v[110:111]
	v_pk_fma_f32 v[112:113], v[88:89], v[54:55], v[112:113]
	ds_read_b128 v[14:17], v94 offset:14688
	v_pk_fma_f32 v[110:111], v[90:91], v[40:41], v[110:111]
	v_pk_fma_f32 v[112:113], v[90:91], v[56:57], v[112:113]
	ds_read_b128 v[10:13], v94 offset:14704
	v_add_f32_e32 v134, v110, v111
	v_add_f32_e32 v135, v112, v113
	v_pk_mul_f32 v[114:115], v[70:71], v[74:75] op_sel_hi:[0,1]
	v_add_f32_dpp v134, v134, v134 quad_perm:[1,0,3,2] row_mask:0xf bank_mask:0xf bound_ctrl:1
	v_add_f32_dpp v135, v135, v135 quad_perm:[1,0,3,2] row_mask:0xf bank_mask:0xf bound_ctrl:1
	v_pk_mul_f32 v[116:117], v[70:71], v[78:79] op_sel_hi:[0,1]
	v_add_f32_dpp v134, v134, v134 quad_perm:[2,3,0,1] row_mask:0xf bank_mask:0xf bound_ctrl:1
	v_add_f32_dpp v135, v135, v135 quad_perm:[2,3,0,1] row_mask:0xf bank_mask:0xf bound_ctrl:1
	ds_read_b32 v73, v95 offset:14912
	v_fma_f32 v134, -v70, v134, v0
	ds_read_b96 v[34:36], v1 offset:15168
	v_mul_f32_e32 v134, v71, v134
	v_mul_f32_e32 v135, v70, v135
	v_pk_mul_f32 v[118:119], v[70:71], v[80:81] op_sel_hi:[0,1]
	v_fma_f32 v135, v72, v134, v135
	v_pk_mul_f32 v[120:121], v[70:71], v[82:83] op_sel_hi:[0,1]
	v_cvt_pk_bf16_f32 v133, v135, v135
	v_pk_mul_f32 v[122:123], v[70:71], v[84:85] op_sel_hi:[0,1]
	v_pk_mul_f32 v[124:125], v[70:71], v[86:87] op_sel_hi:[0,1]
	global_store_short v145, v133, s[100:101]
	v_pk_mul_f32 v[126:127], v[70:71], v[88:89] op_sel_hi:[0,1]
	v_pk_mul_f32 v[128:129], v[70:71], v[90:91] op_sel_hi:[0,1]
	v_pk_fma_f32 v[74:75], v[50:51], v[134:135], v[114:115] op_sel_hi:[1,0,1]
	v_pk_fma_f32 v[78:79], v[52:53], v[134:135], v[116:117] op_sel_hi:[1,0,1]
	v_pk_fma_f32 v[80:81], v[46:47], v[134:135], v[118:119] op_sel_hi:[1,0,1]
	v_pk_fma_f32 v[82:83], v[48:49], v[134:135], v[120:121] op_sel_hi:[1,0,1]
	v_pk_fma_f32 v[84:85], v[42:43], v[134:135], v[122:123] op_sel_hi:[1,0,1]
	v_pk_fma_f32 v[86:87], v[44:45], v[134:135], v[124:125] op_sel_hi:[1,0,1]
	v_pk_fma_f32 v[88:89], v[38:39], v[134:135], v[126:127] op_sel_hi:[1,0,1]
	v_pk_fma_f32 v[90:91], v[40:41], v[134:135], v[128:129] op_sel_hi:[1,0,1]
	s_waitcnt lgkmcnt(0)
	v_pk_fma_f32 v[106:107], v[74:75], v[2:3], 0 op_sel_hi:[1,1,0]
	v_pk_fma_f32 v[108:109], v[74:75], v[30:31], 0 op_sel_hi:[1,1,0]
	ds_read_b128 v[66:69], v94 offset:15200
	v_pk_fma_f32 v[106:107], v[78:79], v[4:5], v[106:107]
	v_pk_fma_f32 v[108:109], v[78:79], v[32:33], v[108:109]
	ds_read_b128 v[62:65], v94 offset:15216
	v_pk_fma_f32 v[106:107], v[80:81], v[6:7], v[106:107]
	v_pk_fma_f32 v[108:109], v[80:81], v[26:27], v[108:109]
	ds_read_b128 v[58:61], v94 offset:15232
	v_pk_fma_f32 v[106:107], v[82:83], v[8:9], v[106:107]
	v_pk_fma_f32 v[108:109], v[82:83], v[28:29], v[108:109]
	ds_read_b128 v[54:57], v94 offset:15248
	v_pk_fma_f32 v[106:107], v[84:85], v[14:15], v[106:107]
	v_pk_fma_f32 v[108:109], v[84:85], v[22:23], v[108:109]
	ds_read_b128 v[50:53], v94 offset:15456
	v_pk_fma_f32 v[106:107], v[86:87], v[16:17], v[106:107]
	v_pk_fma_f32 v[108:109], v[86:87], v[24:25], v[108:109]
	ds_read_b128 v[46:49], v94 offset:15472
	v_pk_fma_f32 v[106:107], v[88:89], v[10:11], v[106:107]
	v_pk_fma_f32 v[108:109], v[88:89], v[18:19], v[108:109]
	ds_read_b128 v[42:45], v94 offset:15488
	v_pk_fma_f32 v[106:107], v[90:91], v[12:13], v[106:107]
	v_pk_fma_f32 v[108:109], v[90:91], v[20:21], v[108:109]
	ds_read_b128 v[38:41], v94 offset:15504
	v_add_f32_e32 v130, v106, v107
	v_add_f32_e32 v131, v108, v109
	v_pk_mul_f32 v[114:115], v[34:35], v[74:75] op_sel_hi:[0,1]
	v_add_f32_dpp v130, v130, v130 quad_perm:[1,0,3,2] row_mask:0xf bank_mask:0xf bound_ctrl:1
	v_add_f32_dpp v131, v131, v131 quad_perm:[1,0,3,2] row_mask:0xf bank_mask:0xf bound_ctrl:1
	v_pk_mul_f32 v[116:117], v[34:35], v[78:79] op_sel_hi:[0,1]
	v_add_f32_dpp v130, v130, v130 quad_perm:[2,3,0,1] row_mask:0xf bank_mask:0xf bound_ctrl:1
	v_add_f32_dpp v131, v131, v131 quad_perm:[2,3,0,1] row_mask:0xf bank_mask:0xf bound_ctrl:1
	ds_read_b32 v0, v95 offset:15712
	v_fma_f32 v130, -v34, v130, v73
	ds_read_b96 v[70:72], v1 offset:15968
	v_mul_f32_e32 v130, v35, v130
	v_mul_f32_e32 v131, v34, v131
	v_pk_mul_f32 v[118:119], v[34:35], v[80:81] op_sel_hi:[0,1]
	v_fma_f32 v131, v36, v130, v131
	v_pk_mul_f32 v[120:121], v[34:35], v[82:83] op_sel_hi:[0,1]
	v_cvt_pk_bf16_f32 v132, v131, v131
	v_pk_mul_f32 v[122:123], v[34:35], v[84:85] op_sel_hi:[0,1]
	v_pk_mul_f32 v[124:125], v[34:35], v[86:87] op_sel_hi:[0,1]
	global_store_short v146, v132, s[100:101]
	v_pk_mul_f32 v[126:127], v[34:35], v[88:89] op_sel_hi:[0,1]
	v_pk_mul_f32 v[128:129], v[34:35], v[90:91] op_sel_hi:[0,1]
	v_pk_fma_f32 v[74:75], v[2:3], v[130:131], v[114:115] op_sel_hi:[1,0,1]
	v_pk_fma_f32 v[78:79], v[4:5], v[130:131], v[116:117] op_sel_hi:[1,0,1]
	v_pk_fma_f32 v[80:81], v[6:7], v[130:131], v[118:119] op_sel_hi:[1,0,1]
	v_pk_fma_f32 v[82:83], v[8:9], v[130:131], v[120:121] op_sel_hi:[1,0,1]
	v_pk_fma_f32 v[84:85], v[14:15], v[130:131], v[122:123] op_sel_hi:[1,0,1]
	v_pk_fma_f32 v[86:87], v[16:17], v[130:131], v[124:125] op_sel_hi:[1,0,1]
	v_pk_fma_f32 v[88:89], v[10:11], v[130:131], v[126:127] op_sel_hi:[1,0,1]
	v_pk_fma_f32 v[90:91], v[12:13], v[130:131], v[128:129] op_sel_hi:[1,0,1]
	s_waitcnt lgkmcnt(0)
	v_pk_fma_f32 v[110:111], v[74:75], v[50:51], 0 op_sel_hi:[1,1,0]
	v_pk_fma_f32 v[112:113], v[74:75], v[66:67], 0 op_sel_hi:[1,1,0]
	ds_read_b128 v[30:33], v94 offset:16000
	v_pk_fma_f32 v[110:111], v[78:79], v[52:53], v[110:111]
	v_pk_fma_f32 v[112:113], v[78:79], v[68:69], v[112:113]
	ds_read_b128 v[26:29], v94 offset:16016
	v_pk_fma_f32 v[110:111], v[80:81], v[46:47], v[110:111]
	v_pk_fma_f32 v[112:113], v[80:81], v[62:63], v[112:113]
	ds_read_b128 v[22:25], v94 offset:16032
	v_pk_fma_f32 v[110:111], v[82:83], v[48:49], v[110:111]
	v_pk_fma_f32 v[112:113], v[82:83], v[64:65], v[112:113]
	ds_read_b128 v[18:21], v94 offset:16048
	v_pk_fma_f32 v[110:111], v[84:85], v[42:43], v[110:111]
	v_pk_fma_f32 v[112:113], v[84:85], v[58:59], v[112:113]
	ds_read_b128 v[2:5], v94 offset:16256
	v_pk_fma_f32 v[110:111], v[86:87], v[44:45], v[110:111]
	v_pk_fma_f32 v[112:113], v[86:87], v[60:61], v[112:113]
	ds_read_b128 v[6:9], v94 offset:16272
	v_pk_fma_f32 v[110:111], v[88:89], v[38:39], v[110:111]
	v_pk_fma_f32 v[112:113], v[88:89], v[54:55], v[112:113]
	ds_read_b128 v[14:17], v94 offset:16288
	v_pk_fma_f32 v[110:111], v[90:91], v[40:41], v[110:111]
	v_pk_fma_f32 v[112:113], v[90:91], v[56:57], v[112:113]
	ds_read_b128 v[10:13], v94 offset:16304
	v_add_f32_e32 v134, v110, v111
	v_add_f32_e32 v135, v112, v113
	v_pk_mul_f32 v[114:115], v[70:71], v[74:75] op_sel_hi:[0,1]
	v_add_f32_dpp v134, v134, v134 quad_perm:[1,0,3,2] row_mask:0xf bank_mask:0xf bound_ctrl:1
	v_add_f32_dpp v135, v135, v135 quad_perm:[1,0,3,2] row_mask:0xf bank_mask:0xf bound_ctrl:1
	v_pk_mul_f32 v[116:117], v[70:71], v[78:79] op_sel_hi:[0,1]
	v_add_f32_dpp v134, v134, v134 quad_perm:[2,3,0,1] row_mask:0xf bank_mask:0xf bound_ctrl:1
	v_add_f32_dpp v135, v135, v135 quad_perm:[2,3,0,1] row_mask:0xf bank_mask:0xf bound_ctrl:1
	ds_read_b32 v73, v95 offset:16512
	v_fma_f32 v134, -v70, v134, v0
	ds_read_b96 v[34:36], v1 offset:16768
	v_mul_f32_e32 v134, v71, v134
	v_mul_f32_e32 v135, v70, v135
	v_pk_mul_f32 v[118:119], v[70:71], v[80:81] op_sel_hi:[0,1]
	v_fma_f32 v135, v72, v134, v135
	v_pk_mul_f32 v[120:121], v[70:71], v[82:83] op_sel_hi:[0,1]
	v_cvt_pk_bf16_f32 v133, v135, v135
	v_pk_mul_f32 v[122:123], v[70:71], v[84:85] op_sel_hi:[0,1]
	v_pk_mul_f32 v[124:125], v[70:71], v[86:87] op_sel_hi:[0,1]
	global_store_short v147, v133, s[100:101]
	v_pk_mul_f32 v[126:127], v[70:71], v[88:89] op_sel_hi:[0,1]
	v_pk_mul_f32 v[128:129], v[70:71], v[90:91] op_sel_hi:[0,1]
	v_pk_fma_f32 v[74:75], v[50:51], v[134:135], v[114:115] op_sel_hi:[1,0,1]
	v_pk_fma_f32 v[78:79], v[52:53], v[134:135], v[116:117] op_sel_hi:[1,0,1]
	v_pk_fma_f32 v[80:81], v[46:47], v[134:135], v[118:119] op_sel_hi:[1,0,1]
	v_pk_fma_f32 v[82:83], v[48:49], v[134:135], v[120:121] op_sel_hi:[1,0,1]
	v_pk_fma_f32 v[84:85], v[42:43], v[134:135], v[122:123] op_sel_hi:[1,0,1]
	v_pk_fma_f32 v[86:87], v[44:45], v[134:135], v[124:125] op_sel_hi:[1,0,1]
	v_pk_fma_f32 v[88:89], v[38:39], v[134:135], v[126:127] op_sel_hi:[1,0,1]
	v_pk_fma_f32 v[90:91], v[40:41], v[134:135], v[128:129] op_sel_hi:[1,0,1]
	s_waitcnt lgkmcnt(0)
	v_pk_fma_f32 v[106:107], v[74:75], v[2:3], 0 op_sel_hi:[1,1,0]
	v_pk_fma_f32 v[108:109], v[74:75], v[30:31], 0 op_sel_hi:[1,1,0]
	ds_read_b128 v[66:69], v94 offset:16800
	v_pk_fma_f32 v[106:107], v[78:79], v[4:5], v[106:107]
	v_pk_fma_f32 v[108:109], v[78:79], v[32:33], v[108:109]
	ds_read_b128 v[62:65], v94 offset:16816
	v_pk_fma_f32 v[106:107], v[80:81], v[6:7], v[106:107]
	v_pk_fma_f32 v[108:109], v[80:81], v[26:27], v[108:109]
	ds_read_b128 v[58:61], v94 offset:16832
	v_pk_fma_f32 v[106:107], v[82:83], v[8:9], v[106:107]
	v_pk_fma_f32 v[108:109], v[82:83], v[28:29], v[108:109]
	ds_read_b128 v[54:57], v94 offset:16848
	v_pk_fma_f32 v[106:107], v[84:85], v[14:15], v[106:107]
	v_pk_fma_f32 v[108:109], v[84:85], v[22:23], v[108:109]
	ds_read_b128 v[50:53], v94 offset:17056
	v_pk_fma_f32 v[106:107], v[86:87], v[16:17], v[106:107]
	v_pk_fma_f32 v[108:109], v[86:87], v[24:25], v[108:109]
	ds_read_b128 v[46:49], v94 offset:17072
	v_pk_fma_f32 v[106:107], v[88:89], v[10:11], v[106:107]
	v_pk_fma_f32 v[108:109], v[88:89], v[18:19], v[108:109]
	ds_read_b128 v[42:45], v94 offset:17088
	v_pk_fma_f32 v[106:107], v[90:91], v[12:13], v[106:107]
	v_pk_fma_f32 v[108:109], v[90:91], v[20:21], v[108:109]
	ds_read_b128 v[38:41], v94 offset:17104
	v_add_f32_e32 v130, v106, v107
	v_add_f32_e32 v131, v108, v109
	v_pk_mul_f32 v[114:115], v[34:35], v[74:75] op_sel_hi:[0,1]
	v_add_f32_dpp v130, v130, v130 quad_perm:[1,0,3,2] row_mask:0xf bank_mask:0xf bound_ctrl:1
	v_add_f32_dpp v131, v131, v131 quad_perm:[1,0,3,2] row_mask:0xf bank_mask:0xf bound_ctrl:1
	v_pk_mul_f32 v[116:117], v[34:35], v[78:79] op_sel_hi:[0,1]
	v_add_f32_dpp v130, v130, v130 quad_perm:[2,3,0,1] row_mask:0xf bank_mask:0xf bound_ctrl:1
	v_add_f32_dpp v131, v131, v131 quad_perm:[2,3,0,1] row_mask:0xf bank_mask:0xf bound_ctrl:1
	ds_read_b32 v0, v95 offset:17312
	v_fma_f32 v130, -v34, v130, v73
	ds_read_b96 v[70:72], v1 offset:17568
	v_mul_f32_e32 v130, v35, v130
	v_mul_f32_e32 v131, v34, v131
	v_pk_mul_f32 v[118:119], v[34:35], v[80:81] op_sel_hi:[0,1]
	v_fma_f32 v131, v36, v130, v131
	v_pk_mul_f32 v[120:121], v[34:35], v[82:83] op_sel_hi:[0,1]
	v_cvt_pk_bf16_f32 v132, v131, v131
	v_pk_mul_f32 v[122:123], v[34:35], v[84:85] op_sel_hi:[0,1]
	v_pk_mul_f32 v[124:125], v[34:35], v[86:87] op_sel_hi:[0,1]
	global_store_short v148, v132, s[100:101]
	v_pk_mul_f32 v[126:127], v[34:35], v[88:89] op_sel_hi:[0,1]
	v_pk_mul_f32 v[128:129], v[34:35], v[90:91] op_sel_hi:[0,1]
	v_pk_fma_f32 v[74:75], v[2:3], v[130:131], v[114:115] op_sel_hi:[1,0,1]
	v_pk_fma_f32 v[78:79], v[4:5], v[130:131], v[116:117] op_sel_hi:[1,0,1]
	v_pk_fma_f32 v[80:81], v[6:7], v[130:131], v[118:119] op_sel_hi:[1,0,1]
	v_pk_fma_f32 v[82:83], v[8:9], v[130:131], v[120:121] op_sel_hi:[1,0,1]
	v_pk_fma_f32 v[84:85], v[14:15], v[130:131], v[122:123] op_sel_hi:[1,0,1]
	v_pk_fma_f32 v[86:87], v[16:17], v[130:131], v[124:125] op_sel_hi:[1,0,1]
	v_pk_fma_f32 v[88:89], v[10:11], v[130:131], v[126:127] op_sel_hi:[1,0,1]
	v_pk_fma_f32 v[90:91], v[12:13], v[130:131], v[128:129] op_sel_hi:[1,0,1]
	s_waitcnt lgkmcnt(0)
	v_pk_fma_f32 v[110:111], v[74:75], v[50:51], 0 op_sel_hi:[1,1,0]
	v_pk_fma_f32 v[112:113], v[74:75], v[66:67], 0 op_sel_hi:[1,1,0]
	ds_read_b128 v[30:33], v94 offset:17600
	v_pk_fma_f32 v[110:111], v[78:79], v[52:53], v[110:111]
	v_pk_fma_f32 v[112:113], v[78:79], v[68:69], v[112:113]
	ds_read_b128 v[26:29], v94 offset:17616
	v_pk_fma_f32 v[110:111], v[80:81], v[46:47], v[110:111]
	v_pk_fma_f32 v[112:113], v[80:81], v[62:63], v[112:113]
	ds_read_b128 v[22:25], v94 offset:17632
	v_pk_fma_f32 v[110:111], v[82:83], v[48:49], v[110:111]
	v_pk_fma_f32 v[112:113], v[82:83], v[64:65], v[112:113]
	ds_read_b128 v[18:21], v94 offset:17648
	v_pk_fma_f32 v[110:111], v[84:85], v[42:43], v[110:111]
	v_pk_fma_f32 v[112:113], v[84:85], v[58:59], v[112:113]
	ds_read_b128 v[2:5], v94 offset:17856
	v_pk_fma_f32 v[110:111], v[86:87], v[44:45], v[110:111]
	v_pk_fma_f32 v[112:113], v[86:87], v[60:61], v[112:113]
	ds_read_b128 v[6:9], v94 offset:17872
	v_pk_fma_f32 v[110:111], v[88:89], v[38:39], v[110:111]
	v_pk_fma_f32 v[112:113], v[88:89], v[54:55], v[112:113]
	ds_read_b128 v[14:17], v94 offset:17888
	v_pk_fma_f32 v[110:111], v[90:91], v[40:41], v[110:111]
	v_pk_fma_f32 v[112:113], v[90:91], v[56:57], v[112:113]
	ds_read_b128 v[10:13], v94 offset:17904
	v_add_f32_e32 v134, v110, v111
	v_add_f32_e32 v135, v112, v113
	v_pk_mul_f32 v[114:115], v[70:71], v[74:75] op_sel_hi:[0,1]
	v_add_f32_dpp v134, v134, v134 quad_perm:[1,0,3,2] row_mask:0xf bank_mask:0xf bound_ctrl:1
	v_add_f32_dpp v135, v135, v135 quad_perm:[1,0,3,2] row_mask:0xf bank_mask:0xf bound_ctrl:1
	v_pk_mul_f32 v[116:117], v[70:71], v[78:79] op_sel_hi:[0,1]
	v_add_f32_dpp v134, v134, v134 quad_perm:[2,3,0,1] row_mask:0xf bank_mask:0xf bound_ctrl:1
	v_add_f32_dpp v135, v135, v135 quad_perm:[2,3,0,1] row_mask:0xf bank_mask:0xf bound_ctrl:1
	ds_read_b32 v73, v95 offset:18112
	v_fma_f32 v134, -v70, v134, v0
	ds_read_b96 v[34:36], v1 offset:18368
	v_mul_f32_e32 v134, v71, v134
	v_mul_f32_e32 v135, v70, v135
	v_pk_mul_f32 v[118:119], v[70:71], v[80:81] op_sel_hi:[0,1]
	v_fma_f32 v135, v72, v134, v135
	v_pk_mul_f32 v[120:121], v[70:71], v[82:83] op_sel_hi:[0,1]
	v_cvt_pk_bf16_f32 v133, v135, v135
	v_pk_mul_f32 v[122:123], v[70:71], v[84:85] op_sel_hi:[0,1]
	v_pk_mul_f32 v[124:125], v[70:71], v[86:87] op_sel_hi:[0,1]
	global_store_short v149, v133, s[100:101]
	v_pk_mul_f32 v[126:127], v[70:71], v[88:89] op_sel_hi:[0,1]
	v_pk_mul_f32 v[128:129], v[70:71], v[90:91] op_sel_hi:[0,1]
	v_pk_fma_f32 v[74:75], v[50:51], v[134:135], v[114:115] op_sel_hi:[1,0,1]
	v_pk_fma_f32 v[78:79], v[52:53], v[134:135], v[116:117] op_sel_hi:[1,0,1]
	v_pk_fma_f32 v[80:81], v[46:47], v[134:135], v[118:119] op_sel_hi:[1,0,1]
	v_pk_fma_f32 v[82:83], v[48:49], v[134:135], v[120:121] op_sel_hi:[1,0,1]
	v_pk_fma_f32 v[84:85], v[42:43], v[134:135], v[122:123] op_sel_hi:[1,0,1]
	v_pk_fma_f32 v[86:87], v[44:45], v[134:135], v[124:125] op_sel_hi:[1,0,1]
	v_pk_fma_f32 v[88:89], v[38:39], v[134:135], v[126:127] op_sel_hi:[1,0,1]
	v_pk_fma_f32 v[90:91], v[40:41], v[134:135], v[128:129] op_sel_hi:[1,0,1]
	s_waitcnt lgkmcnt(0)
	v_pk_fma_f32 v[106:107], v[74:75], v[2:3], 0 op_sel_hi:[1,1,0]
	v_pk_fma_f32 v[108:109], v[74:75], v[30:31], 0 op_sel_hi:[1,1,0]
	ds_read_b128 v[66:69], v94 offset:18400
	v_pk_fma_f32 v[106:107], v[78:79], v[4:5], v[106:107]
	v_pk_fma_f32 v[108:109], v[78:79], v[32:33], v[108:109]
	ds_read_b128 v[62:65], v94 offset:18416
	v_pk_fma_f32 v[106:107], v[80:81], v[6:7], v[106:107]
	v_pk_fma_f32 v[108:109], v[80:81], v[26:27], v[108:109]
	ds_read_b128 v[58:61], v94 offset:18432
	v_pk_fma_f32 v[106:107], v[82:83], v[8:9], v[106:107]
	v_pk_fma_f32 v[108:109], v[82:83], v[28:29], v[108:109]
	ds_read_b128 v[54:57], v94 offset:18448
	v_pk_fma_f32 v[106:107], v[84:85], v[14:15], v[106:107]
	v_pk_fma_f32 v[108:109], v[84:85], v[22:23], v[108:109]
	ds_read_b128 v[50:53], v94 offset:18656
	v_pk_fma_f32 v[106:107], v[86:87], v[16:17], v[106:107]
	v_pk_fma_f32 v[108:109], v[86:87], v[24:25], v[108:109]
	ds_read_b128 v[46:49], v94 offset:18672
	v_pk_fma_f32 v[106:107], v[88:89], v[10:11], v[106:107]
	v_pk_fma_f32 v[108:109], v[88:89], v[18:19], v[108:109]
	ds_read_b128 v[42:45], v94 offset:18688
	v_pk_fma_f32 v[106:107], v[90:91], v[12:13], v[106:107]
	v_pk_fma_f32 v[108:109], v[90:91], v[20:21], v[108:109]
	ds_read_b128 v[38:41], v94 offset:18704
	v_add_f32_e32 v130, v106, v107
	v_add_f32_e32 v131, v108, v109
	v_pk_mul_f32 v[114:115], v[34:35], v[74:75] op_sel_hi:[0,1]
	v_add_f32_dpp v130, v130, v130 quad_perm:[1,0,3,2] row_mask:0xf bank_mask:0xf bound_ctrl:1
	v_add_f32_dpp v131, v131, v131 quad_perm:[1,0,3,2] row_mask:0xf bank_mask:0xf bound_ctrl:1
	v_pk_mul_f32 v[116:117], v[34:35], v[78:79] op_sel_hi:[0,1]
	v_add_f32_dpp v130, v130, v130 quad_perm:[2,3,0,1] row_mask:0xf bank_mask:0xf bound_ctrl:1
	v_add_f32_dpp v131, v131, v131 quad_perm:[2,3,0,1] row_mask:0xf bank_mask:0xf bound_ctrl:1
	ds_read_b32 v0, v95 offset:18912
	v_fma_f32 v130, -v34, v130, v73
	ds_read_b96 v[70:72], v1 offset:19168
	v_mul_f32_e32 v130, v35, v130
	v_mul_f32_e32 v131, v34, v131
	v_pk_mul_f32 v[118:119], v[34:35], v[80:81] op_sel_hi:[0,1]
	v_fma_f32 v131, v36, v130, v131
	v_pk_mul_f32 v[120:121], v[34:35], v[82:83] op_sel_hi:[0,1]
	v_cvt_pk_bf16_f32 v132, v131, v131
	v_pk_mul_f32 v[122:123], v[34:35], v[84:85] op_sel_hi:[0,1]
	v_pk_mul_f32 v[124:125], v[34:35], v[86:87] op_sel_hi:[0,1]
	global_store_short v150, v132, s[100:101]
	v_pk_mul_f32 v[126:127], v[34:35], v[88:89] op_sel_hi:[0,1]
	v_pk_mul_f32 v[128:129], v[34:35], v[90:91] op_sel_hi:[0,1]
	v_pk_fma_f32 v[74:75], v[2:3], v[130:131], v[114:115] op_sel_hi:[1,0,1]
	v_pk_fma_f32 v[78:79], v[4:5], v[130:131], v[116:117] op_sel_hi:[1,0,1]
	v_pk_fma_f32 v[80:81], v[6:7], v[130:131], v[118:119] op_sel_hi:[1,0,1]
	v_pk_fma_f32 v[82:83], v[8:9], v[130:131], v[120:121] op_sel_hi:[1,0,1]
	v_pk_fma_f32 v[84:85], v[14:15], v[130:131], v[122:123] op_sel_hi:[1,0,1]
	v_pk_fma_f32 v[86:87], v[16:17], v[130:131], v[124:125] op_sel_hi:[1,0,1]
	v_pk_fma_f32 v[88:89], v[10:11], v[130:131], v[126:127] op_sel_hi:[1,0,1]
	v_pk_fma_f32 v[90:91], v[12:13], v[130:131], v[128:129] op_sel_hi:[1,0,1]
	s_waitcnt lgkmcnt(0)
	v_pk_fma_f32 v[110:111], v[74:75], v[50:51], 0 op_sel_hi:[1,1,0]
	v_pk_fma_f32 v[112:113], v[74:75], v[66:67], 0 op_sel_hi:[1,1,0]
	ds_read_b128 v[30:33], v94 offset:19200
	v_pk_fma_f32 v[110:111], v[78:79], v[52:53], v[110:111]
	v_pk_fma_f32 v[112:113], v[78:79], v[68:69], v[112:113]
	ds_read_b128 v[26:29], v94 offset:19216
	v_pk_fma_f32 v[110:111], v[80:81], v[46:47], v[110:111]
	v_pk_fma_f32 v[112:113], v[80:81], v[62:63], v[112:113]
	ds_read_b128 v[22:25], v94 offset:19232
	v_pk_fma_f32 v[110:111], v[82:83], v[48:49], v[110:111]
	v_pk_fma_f32 v[112:113], v[82:83], v[64:65], v[112:113]
	ds_read_b128 v[18:21], v94 offset:19248
	v_pk_fma_f32 v[110:111], v[84:85], v[42:43], v[110:111]
	v_pk_fma_f32 v[112:113], v[84:85], v[58:59], v[112:113]
	ds_read_b128 v[2:5], v94 offset:19456
	v_pk_fma_f32 v[110:111], v[86:87], v[44:45], v[110:111]
	v_pk_fma_f32 v[112:113], v[86:87], v[60:61], v[112:113]
	ds_read_b128 v[6:9], v94 offset:19472
	v_pk_fma_f32 v[110:111], v[88:89], v[38:39], v[110:111]
	v_pk_fma_f32 v[112:113], v[88:89], v[54:55], v[112:113]
	ds_read_b128 v[14:17], v94 offset:19488
	v_pk_fma_f32 v[110:111], v[90:91], v[40:41], v[110:111]
	v_pk_fma_f32 v[112:113], v[90:91], v[56:57], v[112:113]
	ds_read_b128 v[10:13], v94 offset:19504
	v_add_f32_e32 v134, v110, v111
	v_add_f32_e32 v135, v112, v113
	v_pk_mul_f32 v[114:115], v[70:71], v[74:75] op_sel_hi:[0,1]
	v_add_f32_dpp v134, v134, v134 quad_perm:[1,0,3,2] row_mask:0xf bank_mask:0xf bound_ctrl:1
	v_add_f32_dpp v135, v135, v135 quad_perm:[1,0,3,2] row_mask:0xf bank_mask:0xf bound_ctrl:1
	v_pk_mul_f32 v[116:117], v[70:71], v[78:79] op_sel_hi:[0,1]
	v_add_f32_dpp v134, v134, v134 quad_perm:[2,3,0,1] row_mask:0xf bank_mask:0xf bound_ctrl:1
	v_add_f32_dpp v135, v135, v135 quad_perm:[2,3,0,1] row_mask:0xf bank_mask:0xf bound_ctrl:1
	ds_read_b32 v73, v95 offset:19712
	v_fma_f32 v134, -v70, v134, v0
	ds_read_b96 v[34:36], v1 offset:19968
	v_mul_f32_e32 v134, v71, v134
	v_mul_f32_e32 v135, v70, v135
	v_pk_mul_f32 v[118:119], v[70:71], v[80:81] op_sel_hi:[0,1]
	v_fma_f32 v135, v72, v134, v135
	v_pk_mul_f32 v[120:121], v[70:71], v[82:83] op_sel_hi:[0,1]
	v_cvt_pk_bf16_f32 v133, v135, v135
	v_pk_mul_f32 v[122:123], v[70:71], v[84:85] op_sel_hi:[0,1]
	v_pk_mul_f32 v[124:125], v[70:71], v[86:87] op_sel_hi:[0,1]
	global_store_short v151, v133, s[100:101]
	v_pk_mul_f32 v[126:127], v[70:71], v[88:89] op_sel_hi:[0,1]
	v_pk_mul_f32 v[128:129], v[70:71], v[90:91] op_sel_hi:[0,1]
	v_pk_fma_f32 v[74:75], v[50:51], v[134:135], v[114:115] op_sel_hi:[1,0,1]
	v_pk_fma_f32 v[78:79], v[52:53], v[134:135], v[116:117] op_sel_hi:[1,0,1]
	v_pk_fma_f32 v[80:81], v[46:47], v[134:135], v[118:119] op_sel_hi:[1,0,1]
	v_pk_fma_f32 v[82:83], v[48:49], v[134:135], v[120:121] op_sel_hi:[1,0,1]
	v_pk_fma_f32 v[84:85], v[42:43], v[134:135], v[122:123] op_sel_hi:[1,0,1]
	v_pk_fma_f32 v[86:87], v[44:45], v[134:135], v[124:125] op_sel_hi:[1,0,1]
	v_pk_fma_f32 v[88:89], v[38:39], v[134:135], v[126:127] op_sel_hi:[1,0,1]
	v_pk_fma_f32 v[90:91], v[40:41], v[134:135], v[128:129] op_sel_hi:[1,0,1]
	s_waitcnt lgkmcnt(0)
	v_pk_fma_f32 v[106:107], v[74:75], v[2:3], 0 op_sel_hi:[1,1,0]
	v_pk_fma_f32 v[108:109], v[74:75], v[30:31], 0 op_sel_hi:[1,1,0]
	ds_read_b128 v[66:69], v94 offset:20000
	v_pk_fma_f32 v[106:107], v[78:79], v[4:5], v[106:107]
	v_pk_fma_f32 v[108:109], v[78:79], v[32:33], v[108:109]
	ds_read_b128 v[62:65], v94 offset:20016
	v_pk_fma_f32 v[106:107], v[80:81], v[6:7], v[106:107]
	v_pk_fma_f32 v[108:109], v[80:81], v[26:27], v[108:109]
	ds_read_b128 v[58:61], v94 offset:20032
	v_pk_fma_f32 v[106:107], v[82:83], v[8:9], v[106:107]
	v_pk_fma_f32 v[108:109], v[82:83], v[28:29], v[108:109]
	ds_read_b128 v[54:57], v94 offset:20048
	v_pk_fma_f32 v[106:107], v[84:85], v[14:15], v[106:107]
	v_pk_fma_f32 v[108:109], v[84:85], v[22:23], v[108:109]
	ds_read_b128 v[50:53], v94 offset:20256
	v_pk_fma_f32 v[106:107], v[86:87], v[16:17], v[106:107]
	v_pk_fma_f32 v[108:109], v[86:87], v[24:25], v[108:109]
	ds_read_b128 v[46:49], v94 offset:20272
	v_pk_fma_f32 v[106:107], v[88:89], v[10:11], v[106:107]
	v_pk_fma_f32 v[108:109], v[88:89], v[18:19], v[108:109]
	ds_read_b128 v[42:45], v94 offset:20288
	v_pk_fma_f32 v[106:107], v[90:91], v[12:13], v[106:107]
	v_pk_fma_f32 v[108:109], v[90:91], v[20:21], v[108:109]
	ds_read_b128 v[38:41], v94 offset:20304
	v_add_f32_e32 v130, v106, v107
	v_add_f32_e32 v131, v108, v109
	v_pk_mul_f32 v[114:115], v[34:35], v[74:75] op_sel_hi:[0,1]
	v_add_f32_dpp v130, v130, v130 quad_perm:[1,0,3,2] row_mask:0xf bank_mask:0xf bound_ctrl:1
	v_add_f32_dpp v131, v131, v131 quad_perm:[1,0,3,2] row_mask:0xf bank_mask:0xf bound_ctrl:1
	v_pk_mul_f32 v[116:117], v[34:35], v[78:79] op_sel_hi:[0,1]
	v_add_f32_dpp v130, v130, v130 quad_perm:[2,3,0,1] row_mask:0xf bank_mask:0xf bound_ctrl:1
	v_add_f32_dpp v131, v131, v131 quad_perm:[2,3,0,1] row_mask:0xf bank_mask:0xf bound_ctrl:1
	ds_read_b32 v0, v95 offset:20512
	v_fma_f32 v130, -v34, v130, v73
	ds_read_b96 v[70:72], v1 offset:20768
	v_mul_f32_e32 v130, v35, v130
	v_mul_f32_e32 v131, v34, v131
	v_pk_mul_f32 v[118:119], v[34:35], v[80:81] op_sel_hi:[0,1]
	v_fma_f32 v131, v36, v130, v131
	v_pk_mul_f32 v[120:121], v[34:35], v[82:83] op_sel_hi:[0,1]
	v_cvt_pk_bf16_f32 v132, v131, v131
	v_pk_mul_f32 v[122:123], v[34:35], v[84:85] op_sel_hi:[0,1]
	v_pk_mul_f32 v[124:125], v[34:35], v[86:87] op_sel_hi:[0,1]
	global_store_short v152, v132, s[100:101]
	v_pk_mul_f32 v[126:127], v[34:35], v[88:89] op_sel_hi:[0,1]
	v_pk_mul_f32 v[128:129], v[34:35], v[90:91] op_sel_hi:[0,1]
	v_pk_fma_f32 v[74:75], v[2:3], v[130:131], v[114:115] op_sel_hi:[1,0,1]
	v_pk_fma_f32 v[78:79], v[4:5], v[130:131], v[116:117] op_sel_hi:[1,0,1]
	v_pk_fma_f32 v[80:81], v[6:7], v[130:131], v[118:119] op_sel_hi:[1,0,1]
	v_pk_fma_f32 v[82:83], v[8:9], v[130:131], v[120:121] op_sel_hi:[1,0,1]
	v_pk_fma_f32 v[84:85], v[14:15], v[130:131], v[122:123] op_sel_hi:[1,0,1]
	v_pk_fma_f32 v[86:87], v[16:17], v[130:131], v[124:125] op_sel_hi:[1,0,1]
	v_pk_fma_f32 v[88:89], v[10:11], v[130:131], v[126:127] op_sel_hi:[1,0,1]
	v_pk_fma_f32 v[90:91], v[12:13], v[130:131], v[128:129] op_sel_hi:[1,0,1]
	s_waitcnt lgkmcnt(0)
	v_pk_fma_f32 v[110:111], v[74:75], v[50:51], 0 op_sel_hi:[1,1,0]
	v_pk_fma_f32 v[112:113], v[74:75], v[66:67], 0 op_sel_hi:[1,1,0]
	ds_read_b128 v[30:33], v94 offset:20800
	v_pk_fma_f32 v[110:111], v[78:79], v[52:53], v[110:111]
	v_pk_fma_f32 v[112:113], v[78:79], v[68:69], v[112:113]
	ds_read_b128 v[26:29], v94 offset:20816
	v_pk_fma_f32 v[110:111], v[80:81], v[46:47], v[110:111]
	v_pk_fma_f32 v[112:113], v[80:81], v[62:63], v[112:113]
	ds_read_b128 v[22:25], v94 offset:20832
	v_pk_fma_f32 v[110:111], v[82:83], v[48:49], v[110:111]
	v_pk_fma_f32 v[112:113], v[82:83], v[64:65], v[112:113]
	ds_read_b128 v[18:21], v94 offset:20848
	v_pk_fma_f32 v[110:111], v[84:85], v[42:43], v[110:111]
	v_pk_fma_f32 v[112:113], v[84:85], v[58:59], v[112:113]
	ds_read_b128 v[2:5], v94 offset:21056
	v_pk_fma_f32 v[110:111], v[86:87], v[44:45], v[110:111]
	v_pk_fma_f32 v[112:113], v[86:87], v[60:61], v[112:113]
	ds_read_b128 v[6:9], v94 offset:21072
	v_pk_fma_f32 v[110:111], v[88:89], v[38:39], v[110:111]
	v_pk_fma_f32 v[112:113], v[88:89], v[54:55], v[112:113]
	ds_read_b128 v[14:17], v94 offset:21088
	v_pk_fma_f32 v[110:111], v[90:91], v[40:41], v[110:111]
	v_pk_fma_f32 v[112:113], v[90:91], v[56:57], v[112:113]
	ds_read_b128 v[10:13], v94 offset:21104
	v_add_f32_e32 v134, v110, v111
	v_add_f32_e32 v135, v112, v113
	v_pk_mul_f32 v[114:115], v[70:71], v[74:75] op_sel_hi:[0,1]
	v_add_f32_dpp v134, v134, v134 quad_perm:[1,0,3,2] row_mask:0xf bank_mask:0xf bound_ctrl:1
	v_add_f32_dpp v135, v135, v135 quad_perm:[1,0,3,2] row_mask:0xf bank_mask:0xf bound_ctrl:1
	v_pk_mul_f32 v[116:117], v[70:71], v[78:79] op_sel_hi:[0,1]
	v_add_f32_dpp v134, v134, v134 quad_perm:[2,3,0,1] row_mask:0xf bank_mask:0xf bound_ctrl:1
	v_add_f32_dpp v135, v135, v135 quad_perm:[2,3,0,1] row_mask:0xf bank_mask:0xf bound_ctrl:1
	ds_read_b32 v73, v95 offset:21312
	v_fma_f32 v134, -v70, v134, v0
	ds_read_b96 v[34:36], v1 offset:21568
	v_mul_f32_e32 v134, v71, v134
	v_mul_f32_e32 v135, v70, v135
	v_pk_mul_f32 v[118:119], v[70:71], v[80:81] op_sel_hi:[0,1]
	v_fma_f32 v135, v72, v134, v135
	v_pk_mul_f32 v[120:121], v[70:71], v[82:83] op_sel_hi:[0,1]
	v_cvt_pk_bf16_f32 v133, v135, v135
	v_pk_mul_f32 v[122:123], v[70:71], v[84:85] op_sel_hi:[0,1]
	v_pk_mul_f32 v[124:125], v[70:71], v[86:87] op_sel_hi:[0,1]
	global_store_short v153, v133, s[100:101]
	v_pk_mul_f32 v[126:127], v[70:71], v[88:89] op_sel_hi:[0,1]
	v_pk_mul_f32 v[128:129], v[70:71], v[90:91] op_sel_hi:[0,1]
	v_pk_fma_f32 v[74:75], v[50:51], v[134:135], v[114:115] op_sel_hi:[1,0,1]
	v_pk_fma_f32 v[78:79], v[52:53], v[134:135], v[116:117] op_sel_hi:[1,0,1]
	v_pk_fma_f32 v[80:81], v[46:47], v[134:135], v[118:119] op_sel_hi:[1,0,1]
	v_pk_fma_f32 v[82:83], v[48:49], v[134:135], v[120:121] op_sel_hi:[1,0,1]
	v_pk_fma_f32 v[84:85], v[42:43], v[134:135], v[122:123] op_sel_hi:[1,0,1]
	v_pk_fma_f32 v[86:87], v[44:45], v[134:135], v[124:125] op_sel_hi:[1,0,1]
	v_pk_fma_f32 v[88:89], v[38:39], v[134:135], v[126:127] op_sel_hi:[1,0,1]
	v_pk_fma_f32 v[90:91], v[40:41], v[134:135], v[128:129] op_sel_hi:[1,0,1]
	s_waitcnt lgkmcnt(0)
	v_pk_fma_f32 v[106:107], v[74:75], v[2:3], 0 op_sel_hi:[1,1,0]
	v_pk_fma_f32 v[108:109], v[74:75], v[30:31], 0 op_sel_hi:[1,1,0]
	ds_read_b128 v[66:69], v94 offset:21600
	v_pk_fma_f32 v[106:107], v[78:79], v[4:5], v[106:107]
	v_pk_fma_f32 v[108:109], v[78:79], v[32:33], v[108:109]
	ds_read_b128 v[62:65], v94 offset:21616
	v_pk_fma_f32 v[106:107], v[80:81], v[6:7], v[106:107]
	v_pk_fma_f32 v[108:109], v[80:81], v[26:27], v[108:109]
	ds_read_b128 v[58:61], v94 offset:21632
	v_pk_fma_f32 v[106:107], v[82:83], v[8:9], v[106:107]
	v_pk_fma_f32 v[108:109], v[82:83], v[28:29], v[108:109]
	ds_read_b128 v[54:57], v94 offset:21648
	v_pk_fma_f32 v[106:107], v[84:85], v[14:15], v[106:107]
	v_pk_fma_f32 v[108:109], v[84:85], v[22:23], v[108:109]
	ds_read_b128 v[50:53], v94 offset:21856
	v_pk_fma_f32 v[106:107], v[86:87], v[16:17], v[106:107]
	v_pk_fma_f32 v[108:109], v[86:87], v[24:25], v[108:109]
	ds_read_b128 v[46:49], v94 offset:21872
	v_pk_fma_f32 v[106:107], v[88:89], v[10:11], v[106:107]
	v_pk_fma_f32 v[108:109], v[88:89], v[18:19], v[108:109]
	ds_read_b128 v[42:45], v94 offset:21888
	v_pk_fma_f32 v[106:107], v[90:91], v[12:13], v[106:107]
	v_pk_fma_f32 v[108:109], v[90:91], v[20:21], v[108:109]
	ds_read_b128 v[38:41], v94 offset:21904
	v_add_f32_e32 v130, v106, v107
	v_add_f32_e32 v131, v108, v109
	v_pk_mul_f32 v[114:115], v[34:35], v[74:75] op_sel_hi:[0,1]
	v_add_f32_dpp v130, v130, v130 quad_perm:[1,0,3,2] row_mask:0xf bank_mask:0xf bound_ctrl:1
	v_add_f32_dpp v131, v131, v131 quad_perm:[1,0,3,2] row_mask:0xf bank_mask:0xf bound_ctrl:1
	v_pk_mul_f32 v[116:117], v[34:35], v[78:79] op_sel_hi:[0,1]
	v_add_f32_dpp v130, v130, v130 quad_perm:[2,3,0,1] row_mask:0xf bank_mask:0xf bound_ctrl:1
	v_add_f32_dpp v131, v131, v131 quad_perm:[2,3,0,1] row_mask:0xf bank_mask:0xf bound_ctrl:1
	ds_read_b32 v0, v95 offset:22112
	v_fma_f32 v130, -v34, v130, v73
	ds_read_b96 v[70:72], v1 offset:22368
	v_mul_f32_e32 v130, v35, v130
	v_mul_f32_e32 v131, v34, v131
	v_pk_mul_f32 v[118:119], v[34:35], v[80:81] op_sel_hi:[0,1]
	v_fma_f32 v131, v36, v130, v131
	v_pk_mul_f32 v[120:121], v[34:35], v[82:83] op_sel_hi:[0,1]
	v_cvt_pk_bf16_f32 v132, v131, v131
	v_pk_mul_f32 v[122:123], v[34:35], v[84:85] op_sel_hi:[0,1]
	v_pk_mul_f32 v[124:125], v[34:35], v[86:87] op_sel_hi:[0,1]
	global_store_short v154, v132, s[100:101]
	v_pk_mul_f32 v[126:127], v[34:35], v[88:89] op_sel_hi:[0,1]
	v_pk_mul_f32 v[128:129], v[34:35], v[90:91] op_sel_hi:[0,1]
	v_pk_fma_f32 v[74:75], v[2:3], v[130:131], v[114:115] op_sel_hi:[1,0,1]
	v_pk_fma_f32 v[78:79], v[4:5], v[130:131], v[116:117] op_sel_hi:[1,0,1]
	v_pk_fma_f32 v[80:81], v[6:7], v[130:131], v[118:119] op_sel_hi:[1,0,1]
	v_pk_fma_f32 v[82:83], v[8:9], v[130:131], v[120:121] op_sel_hi:[1,0,1]
	v_pk_fma_f32 v[84:85], v[14:15], v[130:131], v[122:123] op_sel_hi:[1,0,1]
	v_pk_fma_f32 v[86:87], v[16:17], v[130:131], v[124:125] op_sel_hi:[1,0,1]
	v_pk_fma_f32 v[88:89], v[10:11], v[130:131], v[126:127] op_sel_hi:[1,0,1]
	v_pk_fma_f32 v[90:91], v[12:13], v[130:131], v[128:129] op_sel_hi:[1,0,1]
	s_waitcnt lgkmcnt(0)
	v_pk_fma_f32 v[110:111], v[74:75], v[50:51], 0 op_sel_hi:[1,1,0]
	v_pk_fma_f32 v[112:113], v[74:75], v[66:67], 0 op_sel_hi:[1,1,0]
	ds_read_b128 v[30:33], v94 offset:22400
	v_pk_fma_f32 v[110:111], v[78:79], v[52:53], v[110:111]
	v_pk_fma_f32 v[112:113], v[78:79], v[68:69], v[112:113]
	ds_read_b128 v[26:29], v94 offset:22416
	v_pk_fma_f32 v[110:111], v[80:81], v[46:47], v[110:111]
	v_pk_fma_f32 v[112:113], v[80:81], v[62:63], v[112:113]
	ds_read_b128 v[22:25], v94 offset:22432
	v_pk_fma_f32 v[110:111], v[82:83], v[48:49], v[110:111]
	v_pk_fma_f32 v[112:113], v[82:83], v[64:65], v[112:113]
	ds_read_b128 v[18:21], v94 offset:22448
	v_pk_fma_f32 v[110:111], v[84:85], v[42:43], v[110:111]
	v_pk_fma_f32 v[112:113], v[84:85], v[58:59], v[112:113]
	ds_read_b128 v[2:5], v94 offset:22656
	v_pk_fma_f32 v[110:111], v[86:87], v[44:45], v[110:111]
	v_pk_fma_f32 v[112:113], v[86:87], v[60:61], v[112:113]
	ds_read_b128 v[6:9], v94 offset:22672
	v_pk_fma_f32 v[110:111], v[88:89], v[38:39], v[110:111]
	v_pk_fma_f32 v[112:113], v[88:89], v[54:55], v[112:113]
	ds_read_b128 v[14:17], v94 offset:22688
	v_pk_fma_f32 v[110:111], v[90:91], v[40:41], v[110:111]
	v_pk_fma_f32 v[112:113], v[90:91], v[56:57], v[112:113]
	ds_read_b128 v[10:13], v94 offset:22704
	v_add_f32_e32 v134, v110, v111
	v_add_f32_e32 v135, v112, v113
	v_pk_mul_f32 v[114:115], v[70:71], v[74:75] op_sel_hi:[0,1]
	v_add_f32_dpp v134, v134, v134 quad_perm:[1,0,3,2] row_mask:0xf bank_mask:0xf bound_ctrl:1
	v_add_f32_dpp v135, v135, v135 quad_perm:[1,0,3,2] row_mask:0xf bank_mask:0xf bound_ctrl:1
	v_pk_mul_f32 v[116:117], v[70:71], v[78:79] op_sel_hi:[0,1]
	v_add_f32_dpp v134, v134, v134 quad_perm:[2,3,0,1] row_mask:0xf bank_mask:0xf bound_ctrl:1
	v_add_f32_dpp v135, v135, v135 quad_perm:[2,3,0,1] row_mask:0xf bank_mask:0xf bound_ctrl:1
	ds_read_b32 v73, v95 offset:22912
	v_fma_f32 v134, -v70, v134, v0
	ds_read_b96 v[34:36], v1 offset:23168
	v_mul_f32_e32 v134, v71, v134
	v_mul_f32_e32 v135, v70, v135
	v_pk_mul_f32 v[118:119], v[70:71], v[80:81] op_sel_hi:[0,1]
	v_fma_f32 v135, v72, v134, v135
	v_pk_mul_f32 v[120:121], v[70:71], v[82:83] op_sel_hi:[0,1]
	v_cvt_pk_bf16_f32 v133, v135, v135
	v_pk_mul_f32 v[122:123], v[70:71], v[84:85] op_sel_hi:[0,1]
	v_pk_mul_f32 v[124:125], v[70:71], v[86:87] op_sel_hi:[0,1]
	global_store_short v155, v133, s[100:101]
	v_pk_mul_f32 v[126:127], v[70:71], v[88:89] op_sel_hi:[0,1]
	v_pk_mul_f32 v[128:129], v[70:71], v[90:91] op_sel_hi:[0,1]
	v_pk_fma_f32 v[74:75], v[50:51], v[134:135], v[114:115] op_sel_hi:[1,0,1]
	v_pk_fma_f32 v[78:79], v[52:53], v[134:135], v[116:117] op_sel_hi:[1,0,1]
	v_pk_fma_f32 v[80:81], v[46:47], v[134:135], v[118:119] op_sel_hi:[1,0,1]
	v_pk_fma_f32 v[82:83], v[48:49], v[134:135], v[120:121] op_sel_hi:[1,0,1]
	v_pk_fma_f32 v[84:85], v[42:43], v[134:135], v[122:123] op_sel_hi:[1,0,1]
	v_pk_fma_f32 v[86:87], v[44:45], v[134:135], v[124:125] op_sel_hi:[1,0,1]
	v_pk_fma_f32 v[88:89], v[38:39], v[134:135], v[126:127] op_sel_hi:[1,0,1]
	v_pk_fma_f32 v[90:91], v[40:41], v[134:135], v[128:129] op_sel_hi:[1,0,1]
	s_waitcnt lgkmcnt(0)
	v_pk_fma_f32 v[106:107], v[74:75], v[2:3], 0 op_sel_hi:[1,1,0]
	v_pk_fma_f32 v[108:109], v[74:75], v[30:31], 0 op_sel_hi:[1,1,0]
	ds_read_b128 v[66:69], v94 offset:23200
	v_pk_fma_f32 v[106:107], v[78:79], v[4:5], v[106:107]
	v_pk_fma_f32 v[108:109], v[78:79], v[32:33], v[108:109]
	ds_read_b128 v[62:65], v94 offset:23216
	v_pk_fma_f32 v[106:107], v[80:81], v[6:7], v[106:107]
	v_pk_fma_f32 v[108:109], v[80:81], v[26:27], v[108:109]
	ds_read_b128 v[58:61], v94 offset:23232
	v_pk_fma_f32 v[106:107], v[82:83], v[8:9], v[106:107]
	v_pk_fma_f32 v[108:109], v[82:83], v[28:29], v[108:109]
	ds_read_b128 v[54:57], v94 offset:23248
	v_pk_fma_f32 v[106:107], v[84:85], v[14:15], v[106:107]
	v_pk_fma_f32 v[108:109], v[84:85], v[22:23], v[108:109]
	ds_read_b128 v[50:53], v94 offset:23456
	v_pk_fma_f32 v[106:107], v[86:87], v[16:17], v[106:107]
	v_pk_fma_f32 v[108:109], v[86:87], v[24:25], v[108:109]
	ds_read_b128 v[46:49], v94 offset:23472
	v_pk_fma_f32 v[106:107], v[88:89], v[10:11], v[106:107]
	v_pk_fma_f32 v[108:109], v[88:89], v[18:19], v[108:109]
	ds_read_b128 v[42:45], v94 offset:23488
	v_pk_fma_f32 v[106:107], v[90:91], v[12:13], v[106:107]
	v_pk_fma_f32 v[108:109], v[90:91], v[20:21], v[108:109]
	ds_read_b128 v[38:41], v94 offset:23504
	v_add_f32_e32 v130, v106, v107
	v_add_f32_e32 v131, v108, v109
	v_pk_mul_f32 v[114:115], v[34:35], v[74:75] op_sel_hi:[0,1]
	v_add_f32_dpp v130, v130, v130 quad_perm:[1,0,3,2] row_mask:0xf bank_mask:0xf bound_ctrl:1
	v_add_f32_dpp v131, v131, v131 quad_perm:[1,0,3,2] row_mask:0xf bank_mask:0xf bound_ctrl:1
	v_pk_mul_f32 v[116:117], v[34:35], v[78:79] op_sel_hi:[0,1]
	v_add_f32_dpp v130, v130, v130 quad_perm:[2,3,0,1] row_mask:0xf bank_mask:0xf bound_ctrl:1
	v_add_f32_dpp v131, v131, v131 quad_perm:[2,3,0,1] row_mask:0xf bank_mask:0xf bound_ctrl:1
	ds_read_b32 v0, v95 offset:23712
	v_fma_f32 v130, -v34, v130, v73
	ds_read_b96 v[70:72], v1 offset:23968
	v_mul_f32_e32 v130, v35, v130
	v_mul_f32_e32 v131, v34, v131
	v_pk_mul_f32 v[118:119], v[34:35], v[80:81] op_sel_hi:[0,1]
	v_fma_f32 v131, v36, v130, v131
	v_pk_mul_f32 v[120:121], v[34:35], v[82:83] op_sel_hi:[0,1]
	v_cvt_pk_bf16_f32 v132, v131, v131
	v_pk_mul_f32 v[122:123], v[34:35], v[84:85] op_sel_hi:[0,1]
	v_pk_mul_f32 v[124:125], v[34:35], v[86:87] op_sel_hi:[0,1]
	global_store_short v156, v132, s[100:101]
	v_pk_mul_f32 v[126:127], v[34:35], v[88:89] op_sel_hi:[0,1]
	v_pk_mul_f32 v[128:129], v[34:35], v[90:91] op_sel_hi:[0,1]
	v_pk_fma_f32 v[74:75], v[2:3], v[130:131], v[114:115] op_sel_hi:[1,0,1]
	v_pk_fma_f32 v[78:79], v[4:5], v[130:131], v[116:117] op_sel_hi:[1,0,1]
	v_pk_fma_f32 v[80:81], v[6:7], v[130:131], v[118:119] op_sel_hi:[1,0,1]
	v_pk_fma_f32 v[82:83], v[8:9], v[130:131], v[120:121] op_sel_hi:[1,0,1]
	v_pk_fma_f32 v[84:85], v[14:15], v[130:131], v[122:123] op_sel_hi:[1,0,1]
	v_pk_fma_f32 v[86:87], v[16:17], v[130:131], v[124:125] op_sel_hi:[1,0,1]
	v_pk_fma_f32 v[88:89], v[10:11], v[130:131], v[126:127] op_sel_hi:[1,0,1]
	v_pk_fma_f32 v[90:91], v[12:13], v[130:131], v[128:129] op_sel_hi:[1,0,1]
	s_waitcnt lgkmcnt(0)
	v_pk_fma_f32 v[110:111], v[74:75], v[50:51], 0 op_sel_hi:[1,1,0]
	v_pk_fma_f32 v[112:113], v[74:75], v[66:67], 0 op_sel_hi:[1,1,0]
	ds_read_b128 v[30:33], v94 offset:24000
	v_pk_fma_f32 v[110:111], v[78:79], v[52:53], v[110:111]
	v_pk_fma_f32 v[112:113], v[78:79], v[68:69], v[112:113]
	ds_read_b128 v[26:29], v94 offset:24016
	v_pk_fma_f32 v[110:111], v[80:81], v[46:47], v[110:111]
	v_pk_fma_f32 v[112:113], v[80:81], v[62:63], v[112:113]
	ds_read_b128 v[22:25], v94 offset:24032
	v_pk_fma_f32 v[110:111], v[82:83], v[48:49], v[110:111]
	v_pk_fma_f32 v[112:113], v[82:83], v[64:65], v[112:113]
	ds_read_b128 v[18:21], v94 offset:24048
	v_pk_fma_f32 v[110:111], v[84:85], v[42:43], v[110:111]
	v_pk_fma_f32 v[112:113], v[84:85], v[58:59], v[112:113]
	ds_read_b128 v[2:5], v94 offset:24256
	v_pk_fma_f32 v[110:111], v[86:87], v[44:45], v[110:111]
	v_pk_fma_f32 v[112:113], v[86:87], v[60:61], v[112:113]
	ds_read_b128 v[6:9], v94 offset:24272
	v_pk_fma_f32 v[110:111], v[88:89], v[38:39], v[110:111]
	v_pk_fma_f32 v[112:113], v[88:89], v[54:55], v[112:113]
	ds_read_b128 v[14:17], v94 offset:24288
	v_pk_fma_f32 v[110:111], v[90:91], v[40:41], v[110:111]
	v_pk_fma_f32 v[112:113], v[90:91], v[56:57], v[112:113]
	ds_read_b128 v[10:13], v94 offset:24304
	v_add_f32_e32 v134, v110, v111
	v_add_f32_e32 v135, v112, v113
	v_pk_mul_f32 v[114:115], v[70:71], v[74:75] op_sel_hi:[0,1]
	v_add_f32_dpp v134, v134, v134 quad_perm:[1,0,3,2] row_mask:0xf bank_mask:0xf bound_ctrl:1
	v_add_f32_dpp v135, v135, v135 quad_perm:[1,0,3,2] row_mask:0xf bank_mask:0xf bound_ctrl:1
	v_pk_mul_f32 v[116:117], v[70:71], v[78:79] op_sel_hi:[0,1]
	v_add_f32_dpp v134, v134, v134 quad_perm:[2,3,0,1] row_mask:0xf bank_mask:0xf bound_ctrl:1
	v_add_f32_dpp v135, v135, v135 quad_perm:[2,3,0,1] row_mask:0xf bank_mask:0xf bound_ctrl:1
	ds_read_b32 v73, v95 offset:24512
	v_fma_f32 v134, -v70, v134, v0
	ds_read_b96 v[34:36], v1 offset:24768
	v_mul_f32_e32 v134, v71, v134
	v_mul_f32_e32 v135, v70, v135
	v_pk_mul_f32 v[118:119], v[70:71], v[80:81] op_sel_hi:[0,1]
	v_fma_f32 v135, v72, v134, v135
	v_pk_mul_f32 v[120:121], v[70:71], v[82:83] op_sel_hi:[0,1]
	v_cvt_pk_bf16_f32 v133, v135, v135
	v_pk_mul_f32 v[122:123], v[70:71], v[84:85] op_sel_hi:[0,1]
	v_pk_mul_f32 v[124:125], v[70:71], v[86:87] op_sel_hi:[0,1]
	global_store_short v157, v133, s[100:101]
	v_pk_mul_f32 v[126:127], v[70:71], v[88:89] op_sel_hi:[0,1]
	v_pk_mul_f32 v[128:129], v[70:71], v[90:91] op_sel_hi:[0,1]
	v_pk_fma_f32 v[74:75], v[50:51], v[134:135], v[114:115] op_sel_hi:[1,0,1]
	v_pk_fma_f32 v[78:79], v[52:53], v[134:135], v[116:117] op_sel_hi:[1,0,1]
	v_pk_fma_f32 v[80:81], v[46:47], v[134:135], v[118:119] op_sel_hi:[1,0,1]
	v_pk_fma_f32 v[82:83], v[48:49], v[134:135], v[120:121] op_sel_hi:[1,0,1]
	v_pk_fma_f32 v[84:85], v[42:43], v[134:135], v[122:123] op_sel_hi:[1,0,1]
	v_pk_fma_f32 v[86:87], v[44:45], v[134:135], v[124:125] op_sel_hi:[1,0,1]
	v_pk_fma_f32 v[88:89], v[38:39], v[134:135], v[126:127] op_sel_hi:[1,0,1]
	v_pk_fma_f32 v[90:91], v[40:41], v[134:135], v[128:129] op_sel_hi:[1,0,1]
	s_waitcnt lgkmcnt(0)
	v_pk_fma_f32 v[106:107], v[74:75], v[2:3], 0 op_sel_hi:[1,1,0]
	v_pk_fma_f32 v[108:109], v[74:75], v[30:31], 0 op_sel_hi:[1,1,0]
	ds_read_b128 v[66:69], v94 offset:24800
	v_pk_fma_f32 v[106:107], v[78:79], v[4:5], v[106:107]
	v_pk_fma_f32 v[108:109], v[78:79], v[32:33], v[108:109]
	ds_read_b128 v[62:65], v94 offset:24816
	v_pk_fma_f32 v[106:107], v[80:81], v[6:7], v[106:107]
	v_pk_fma_f32 v[108:109], v[80:81], v[26:27], v[108:109]
	ds_read_b128 v[58:61], v94 offset:24832
	v_pk_fma_f32 v[106:107], v[82:83], v[8:9], v[106:107]
	v_pk_fma_f32 v[108:109], v[82:83], v[28:29], v[108:109]
	ds_read_b128 v[54:57], v94 offset:24848
	v_pk_fma_f32 v[106:107], v[84:85], v[14:15], v[106:107]
	v_pk_fma_f32 v[108:109], v[84:85], v[22:23], v[108:109]
	ds_read_b128 v[50:53], v94 offset:25056
	v_pk_fma_f32 v[106:107], v[86:87], v[16:17], v[106:107]
	v_pk_fma_f32 v[108:109], v[86:87], v[24:25], v[108:109]
	ds_read_b128 v[46:49], v94 offset:25072
	v_pk_fma_f32 v[106:107], v[88:89], v[10:11], v[106:107]
	v_pk_fma_f32 v[108:109], v[88:89], v[18:19], v[108:109]
	ds_read_b128 v[42:45], v94 offset:25088
	v_pk_fma_f32 v[106:107], v[90:91], v[12:13], v[106:107]
	v_pk_fma_f32 v[108:109], v[90:91], v[20:21], v[108:109]
	ds_read_b128 v[38:41], v94 offset:25104
	v_add_f32_e32 v130, v106, v107
	v_add_f32_e32 v131, v108, v109
	v_pk_mul_f32 v[114:115], v[34:35], v[74:75] op_sel_hi:[0,1]
	v_add_f32_dpp v130, v130, v130 quad_perm:[1,0,3,2] row_mask:0xf bank_mask:0xf bound_ctrl:1
	v_add_f32_dpp v131, v131, v131 quad_perm:[1,0,3,2] row_mask:0xf bank_mask:0xf bound_ctrl:1
	v_pk_mul_f32 v[116:117], v[34:35], v[78:79] op_sel_hi:[0,1]
	v_add_f32_dpp v130, v130, v130 quad_perm:[2,3,0,1] row_mask:0xf bank_mask:0xf bound_ctrl:1
	v_add_f32_dpp v131, v131, v131 quad_perm:[2,3,0,1] row_mask:0xf bank_mask:0xf bound_ctrl:1
	ds_read_b32 v0, v95 offset:25312
	v_fma_f32 v130, -v34, v130, v73
	ds_read_b96 v[70:72], v1 offset:25568
	v_mul_f32_e32 v130, v35, v130
	v_mul_f32_e32 v131, v34, v131
	v_pk_mul_f32 v[118:119], v[34:35], v[80:81] op_sel_hi:[0,1]
	v_fma_f32 v131, v36, v130, v131
	v_pk_mul_f32 v[120:121], v[34:35], v[82:83] op_sel_hi:[0,1]
	v_cvt_pk_bf16_f32 v132, v131, v131
	v_pk_mul_f32 v[122:123], v[34:35], v[84:85] op_sel_hi:[0,1]
	v_pk_mul_f32 v[124:125], v[34:35], v[86:87] op_sel_hi:[0,1]
	global_store_short v158, v132, s[100:101]
	v_pk_mul_f32 v[126:127], v[34:35], v[88:89] op_sel_hi:[0,1]
	v_pk_mul_f32 v[128:129], v[34:35], v[90:91] op_sel_hi:[0,1]
	v_pk_fma_f32 v[74:75], v[2:3], v[130:131], v[114:115] op_sel_hi:[1,0,1]
	v_pk_fma_f32 v[78:79], v[4:5], v[130:131], v[116:117] op_sel_hi:[1,0,1]
	v_pk_fma_f32 v[80:81], v[6:7], v[130:131], v[118:119] op_sel_hi:[1,0,1]
	v_pk_fma_f32 v[82:83], v[8:9], v[130:131], v[120:121] op_sel_hi:[1,0,1]
	v_pk_fma_f32 v[84:85], v[14:15], v[130:131], v[122:123] op_sel_hi:[1,0,1]
	v_pk_fma_f32 v[86:87], v[16:17], v[130:131], v[124:125] op_sel_hi:[1,0,1]
	v_pk_fma_f32 v[88:89], v[10:11], v[130:131], v[126:127] op_sel_hi:[1,0,1]
	v_pk_fma_f32 v[90:91], v[12:13], v[130:131], v[128:129] op_sel_hi:[1,0,1]
	s_waitcnt lgkmcnt(0)
	v_pk_fma_f32 v[110:111], v[74:75], v[50:51], 0 op_sel_hi:[1,1,0]
	v_pk_fma_f32 v[112:113], v[74:75], v[66:67], 0 op_sel_hi:[1,1,0]
	ds_read_b128 v[30:33], v94 offset:25600
	v_pk_fma_f32 v[110:111], v[78:79], v[52:53], v[110:111]
	v_pk_fma_f32 v[112:113], v[78:79], v[68:69], v[112:113]
	ds_read_b128 v[26:29], v94 offset:25616
	v_pk_fma_f32 v[110:111], v[80:81], v[46:47], v[110:111]
	v_pk_fma_f32 v[112:113], v[80:81], v[62:63], v[112:113]
	ds_read_b128 v[22:25], v94 offset:25632
	v_pk_fma_f32 v[110:111], v[82:83], v[48:49], v[110:111]
	v_pk_fma_f32 v[112:113], v[82:83], v[64:65], v[112:113]
	ds_read_b128 v[18:21], v94 offset:25648
	v_pk_fma_f32 v[110:111], v[84:85], v[42:43], v[110:111]
	v_pk_fma_f32 v[112:113], v[84:85], v[58:59], v[112:113]
	ds_read_b128 v[2:5], v94 offset:25856
	v_pk_fma_f32 v[110:111], v[86:87], v[44:45], v[110:111]
	v_pk_fma_f32 v[112:113], v[86:87], v[60:61], v[112:113]
	ds_read_b128 v[6:9], v94 offset:25872
	v_pk_fma_f32 v[110:111], v[88:89], v[38:39], v[110:111]
	v_pk_fma_f32 v[112:113], v[88:89], v[54:55], v[112:113]
	ds_read_b128 v[14:17], v94 offset:25888
	v_pk_fma_f32 v[110:111], v[90:91], v[40:41], v[110:111]
	v_pk_fma_f32 v[112:113], v[90:91], v[56:57], v[112:113]
	ds_read_b128 v[10:13], v94 offset:25904
	v_add_f32_e32 v134, v110, v111
	v_add_f32_e32 v135, v112, v113
	v_pk_mul_f32 v[114:115], v[70:71], v[74:75] op_sel_hi:[0,1]
	v_add_f32_dpp v134, v134, v134 quad_perm:[1,0,3,2] row_mask:0xf bank_mask:0xf bound_ctrl:1
	v_add_f32_dpp v135, v135, v135 quad_perm:[1,0,3,2] row_mask:0xf bank_mask:0xf bound_ctrl:1
	v_pk_mul_f32 v[116:117], v[70:71], v[78:79] op_sel_hi:[0,1]
	v_add_f32_dpp v134, v134, v134 quad_perm:[2,3,0,1] row_mask:0xf bank_mask:0xf bound_ctrl:1
	v_add_f32_dpp v135, v135, v135 quad_perm:[2,3,0,1] row_mask:0xf bank_mask:0xf bound_ctrl:1
	ds_read_b32 v73, v95 offset:26112
	v_fma_f32 v134, -v70, v134, v0
	ds_read_b96 v[34:36], v1 offset:26368
	v_mul_f32_e32 v134, v71, v134
	v_mul_f32_e32 v135, v70, v135
	v_pk_mul_f32 v[118:119], v[70:71], v[80:81] op_sel_hi:[0,1]
	v_fma_f32 v135, v72, v134, v135
	v_pk_mul_f32 v[120:121], v[70:71], v[82:83] op_sel_hi:[0,1]
	v_cvt_pk_bf16_f32 v133, v135, v135
	v_pk_mul_f32 v[122:123], v[70:71], v[84:85] op_sel_hi:[0,1]
	v_pk_mul_f32 v[124:125], v[70:71], v[86:87] op_sel_hi:[0,1]
	global_store_short v159, v133, s[100:101]
	v_pk_mul_f32 v[126:127], v[70:71], v[88:89] op_sel_hi:[0,1]
	v_pk_mul_f32 v[128:129], v[70:71], v[90:91] op_sel_hi:[0,1]
	v_pk_fma_f32 v[74:75], v[50:51], v[134:135], v[114:115] op_sel_hi:[1,0,1]
	v_pk_fma_f32 v[78:79], v[52:53], v[134:135], v[116:117] op_sel_hi:[1,0,1]
	v_pk_fma_f32 v[80:81], v[46:47], v[134:135], v[118:119] op_sel_hi:[1,0,1]
	v_pk_fma_f32 v[82:83], v[48:49], v[134:135], v[120:121] op_sel_hi:[1,0,1]
	v_pk_fma_f32 v[84:85], v[42:43], v[134:135], v[122:123] op_sel_hi:[1,0,1]
	v_pk_fma_f32 v[86:87], v[44:45], v[134:135], v[124:125] op_sel_hi:[1,0,1]
	v_pk_fma_f32 v[88:89], v[38:39], v[134:135], v[126:127] op_sel_hi:[1,0,1]
	v_pk_fma_f32 v[90:91], v[40:41], v[134:135], v[128:129] op_sel_hi:[1,0,1]
	s_branch .LBB0_899
